# pool and fourier-out: hoist loop-invariant weight loads (load+vmcnt(0)+mfma chains) out of the item loops, on top of gmlp hoist + GEMM peel
# speedup vs baseline: 1.0205x; 1.0031x over previous
.LBB0_233:
	v_mov_b32_e32 v0, v242
	s_load_dword s11, s[54:55], 0x0
	s_mov_b32 s9, s76
	v_readfirstlane_b32 s0, v0
	s_waitcnt lgkmcnt(0)
	s_ashr_i32 s17, s0, 6
	s_lshl_b32 s0, s9, 3
	s_lshl_b32 s2, s56, 19
	s_add_i32 s0, s0, s17
	s_cmpk_gt_i32 s0, 0xfff
	s_cbranch_scc1 .LBB0_237
	s_lshl_b32 s3, s11, 3
	v_readlane_b32 s16, v253, 8
	v_and_b32_e32 v136, 15, v0
	s_add_u32 s18, s16, s2
	v_readlane_b32 s16, v253, 9
	s_mul_i32 s20, s17, 0x4200
	s_addc_u32 s19, s16, 0
	s_add_i32 s20, s20, 0
	v_mul_u32_u24_e32 v3, 0x210, v136
	v_and_b32_e32 v208, 48, v0
	v_lshl_add_u64 v[4:5], s[18:19], 0, v[208:209]
	v_add3_u32 v149, s20, v3, v208
	v_lshlrev_b32_e32 v208, 7, v136
	v_lshl_add_u64 v[72:73], v[4:5], 0, v[208:209]
	s_mov_b64 s[18:19], 0x1800
	v_lshl_add_u64 v[76:77], v[72:73], 0, s[18:19]
	s_mov_b64 s[18:19], 0x1040
	v_lshl_add_u64 v[78:79], v[72:73], 0, s[18:19]
	s_mov_b64 s[18:19], 0x1840
	v_lshl_add_u64 v[80:81], v[72:73], 0, s[18:19]
	s_mov_b64 s[18:19], 0x2000
	v_lshl_add_u64 v[82:83], v[72:73], 0, s[18:19]
	s_mov_b64 s[18:19], 0x2800
	v_lshl_add_u64 v[84:85], v[72:73], 0, s[18:19]
	s_mov_b64 s[18:19], 0x3000
	v_lshl_add_u64 v[86:87], v[72:73], 0, s[18:19]
	s_mov_b64 s[18:19], 0x3800
	v_lshl_add_u64 v[88:89], v[72:73], 0, s[18:19]
	s_mov_b64 s[18:19], 0x2040
	v_lshl_add_u64 v[90:91], v[72:73], 0, s[18:19]
	s_mov_b64 s[18:19], 0x2840
	v_lshl_add_u64 v[92:93], v[72:73], 0, s[18:19]
	s_mov_b64 s[18:19], 0x3040
	v_lshl_add_u64 v[94:95], v[72:73], 0, s[18:19]
	s_mov_b64 s[18:19], 0x3840
	v_lshl_add_u64 v[96:97], v[72:73], 0, s[18:19]
	s_mov_b64 s[18:19], 0x4000
	v_lshl_add_u64 v[98:99], v[72:73], 0, s[18:19]
	s_mov_b64 s[18:19], 0x4800
	v_lshl_add_u64 v[100:101], v[72:73], 0, s[18:19]
	s_mov_b64 s[18:19], 0x5000
	v_lshl_add_u64 v[102:103], v[72:73], 0, s[18:19]
	s_mov_b64 s[18:19], 0x5800
	v_lshl_add_u64 v[104:105], v[72:73], 0, s[18:19]
	s_mov_b64 s[18:19], 0x4040
	v_lshl_add_u64 v[106:107], v[72:73], 0, s[18:19]
	s_mov_b64 s[18:19], 0x4840
	v_lshl_add_u64 v[108:109], v[72:73], 0, s[18:19]
	s_mov_b64 s[18:19], 0x5040
	v_lshl_add_u64 v[110:111], v[72:73], 0, s[18:19]
	s_mov_b64 s[18:19], 0x5840
	v_lshl_add_u64 v[112:113], v[72:73], 0, s[18:19]
	s_mov_b64 s[18:19], 0x6000
	v_lshl_add_u64 v[114:115], v[72:73], 0, s[18:19]
	s_mov_b64 s[18:19], 0x6800
	v_lshl_add_u64 v[116:117], v[72:73], 0, s[18:19]
	s_mov_b64 s[18:19], 0x7000
	v_lshl_add_u64 v[118:119], v[72:73], 0, s[18:19]
	s_mov_b64 s[18:19], 0x7800
	v_lshlrev_b32_e32 v1, 3, v0
	v_lshl_add_u64 v[120:121], v[72:73], 0, s[18:19]
	s_mov_b64 s[18:19], 0x6040
	v_and_b32_e32 v2, 0xf8, v1
	v_lshlrev_b32_e32 v1, 4, v0
	v_lshl_add_u64 v[122:123], v[72:73], 0, s[18:19]
	s_mov_b64 s[18:19], 0x6840
	v_bfe_u32 v137, v0, 5, 1
	v_and_b32_e32 v1, 0x1f0, v1
	v_lshrrev_b32_e32 v0, 2, v0
	v_lshl_add_u64 v[124:125], v[72:73], 0, s[18:19]
	s_mov_b64 s[18:19], 0x7040
	v_add_u32_e32 v1, s20, v1
	v_and_b32_e32 v0, 12, v0
	v_mul_u32_u24_e32 v6, 0x210, v137
	v_lshl_add_u64 v[126:127], v[72:73], 0, s[18:19]
	s_mov_b64 s[18:19], 0x7840
	s_lshl_b32 s9, s9, 7
	s_lshl_b32 s17, s17, 4
	v_or_b32_e32 v138, 10, v137
	v_or_b32_e32 v139, 12, v137
	v_or_b32_e32 v140, 14, v137
	v_or_b32_e32 v141, 16, v137
	v_or_b32_e32 v142, 18, v137
	v_or_b32_e32 v143, 20, v137
	v_or_b32_e32 v144, 22, v137
	v_or_b32_e32 v145, 24, v137
	v_or_b32_e32 v146, 26, v137
	v_or_b32_e32 v147, 28, v137
	v_or_b32_e32 v148, 30, v137
	v_lshl_add_u64 v[74:75], v[72:73], 0, s[38:39]
	v_lshl_add_u64 v[128:129], v[72:73], 0, s[18:19]
	s_add_i32 s9, s9, s17
	s_lshl_b32 s17, s11, 7
	v_lshlrev_b32_e32 v130, 1, v2
	v_add_u32_e32 v150, v1, v6
	v_lshlrev_b32_e32 v132, 1, v0
	s_mov_b32 s16, 0xbff9000
	global_load_dwordx4 v[166:169], v[72:73], off offset:64
	global_load_dwordx4 v[170:173], v[72:73], off offset:2112
	global_load_dwordx4 v[174:177], v[78:79], off
	global_load_dwordx4 v[178:181], v[80:81], off
	global_load_dwordx4 v[182:185], v[90:91], off
	global_load_dwordx4 v[186:189], v[92:93], off
	global_load_dwordx4 v[190:193], v[94:95], off
	global_load_dwordx4 v[194:197], v[96:97], off
	global_load_dwordx4 v[198:201], v[106:107], off
	global_load_dwordx4 v[202:205], v[108:109], off
	global_load_dwordx4 v[214:217], v[110:111], off
	global_load_dwordx4 v[218:221], v[112:113], off
	global_load_dwordx4 v[222:225], v[122:123], off
	global_load_dwordx4 v[226:229], v[124:125], off
	global_load_dwordx4 v[230:233], v[126:127], off
	global_load_dwordx4 v[234:237], v[128:129], off
	s_waitcnt vmcnt(0)
.LBB0_235:
	v_add_u32_e32 v56, s9, v137
	v_max_i32_e32 v0, 8, v56
	v_add_u32_e32 v4, 2, v56
	v_mul_lo_u32 v0, v0, s6
	v_max_i32_e32 v4, 8, v4
	v_add_u32_e32 v208, 0xffff9000, v0
	v_mul_lo_u32 v4, v4, s6
	v_add_u32_e32 v8, 4, v56
	v_lshl_add_u64 v[0:1], s[84:85], 0, v[208:209]
	v_add_u32_e32 v208, 0xffff9000, v4
	v_max_i32_e32 v8, 8, v8
	v_mov_b32_e32 v131, v209
	v_lshl_add_u64 v[4:5], s[84:85], 0, v[208:209]
	v_mul_lo_u32 v8, v8, s6
	v_add_u32_e32 v12, 6, v56
	v_lshl_add_u64 v[4:5], v[4:5], 0, v[130:131]
	v_add_u32_e32 v208, 0xffff9000, v8
	v_max_i32_e32 v12, 8, v12
	v_add_co_u32_e64 v4, s[36:37], s58, v4
	v_lshl_add_u64 v[8:9], s[84:85], 0, v[208:209]
	v_mul_lo_u32 v12, v12, s6
	v_addc_co_u32_e64 v5, s[36:37], 0, v5, s[36:37]
	v_lshl_add_u64 v[8:9], v[8:9], 0, v[130:131]
	v_add_u32_e32 v208, 0xffff9000, v12
	v_add_co_u32_e64 v8, s[36:37], s58, v8
	v_lshl_add_u64 v[12:13], s[84:85], 0, v[208:209]
	v_lshl_add_u64 v[0:1], v[0:1], 0, v[130:131]
	v_addc_co_u32_e64 v9, s[36:37], 0, v9, s[36:37]
	v_lshl_add_u64 v[12:13], v[12:13], 0, v[130:131]
	v_add_co_u32_e32 v0, vcc, s58, v0
	v_add_co_u32_e64 v12, s[36:37], s58, v12
	s_nop 0
	v_addc_co_u32_e32 v1, vcc, 0, v1, vcc
	v_addc_co_u32_e64 v13, s[36:37], 0, v13, s[36:37]
	global_load_dwordx4 v[0:3], v[0:1], off offset:1536
	s_ashr_i32 s11, s9, 31
	global_load_dwordx4 v[4:7], v[4:5], off offset:1536
	s_lshr_b32 s11, s11, 19
	global_load_dwordx4 v[8:11], v[8:9], off offset:1536
	s_add_i32 s11, s9, s11
	global_load_dwordx4 v[12:15], v[12:13], off offset:1536
	v_add_u32_e32 v16, 8, v56
	s_and_b32 s11, s11, 0xffffe000
	v_max_i32_e32 v16, 8, v16
	s_sub_i32 s11, s9, s11
	v_mul_lo_u32 v16, v16, s6
	s_add_i32 s18, s11, -8
	v_add_u32_e32 v208, 0xffff9000, v16
	s_cmpk_lt_u32 s18, 0x2000
	v_lshl_add_u64 v[16:17], s[84:85], 0, v[208:209]
	s_cselect_b64 vcc, -1, 0
	v_lshl_add_u64 v[16:17], v[16:17], 0, v[130:131]
	v_add_u32_e32 v20, 10, v56
	v_max_i32_e32 v20, 8, v20
	v_mul_lo_u32 v20, v20, s6
	v_add_u32_e32 v208, 0xffff9000, v20
	s_cmp_gt_i32 s11, -1
	v_lshl_add_u64 v[20:21], s[84:85], 0, v[208:209]
	v_lshl_add_u64 v[20:21], v[20:21], 0, v[130:131]
	v_add_u32_e32 v24, s18, v138
	v_add_u32_e32 v28, s18, v139
	v_add_u32_e32 v32, s18, v140
	v_add_u32_e32 v36, s18, v141
	v_add_u32_e32 v40, s18, v142
	v_add_u32_e32 v44, s18, v143
	v_add_u32_e32 v48, s18, v144
	v_add_u32_e32 v52, s18, v145
	v_add_u32_e32 v57, s18, v146
	s_waitcnt vmcnt(3)
	v_cndmask_b32_e32 v3, 0, v3, vcc
	v_cndmask_b32_e32 v2, 0, v2, vcc
	v_cndmask_b32_e32 v1, 0, v1, vcc
	v_cndmask_b32_e32 v0, 0, v0, vcc
	s_waitcnt vmcnt(2)
	v_cndmask_b32_e32 v7, 0, v7, vcc
	v_cndmask_b32_e32 v6, 0, v6, vcc
	v_cndmask_b32_e32 v5, 0, v5, vcc
	v_cndmask_b32_e32 v4, 0, v4, vcc
	s_waitcnt vmcnt(1)
	v_cndmask_b32_e32 v11, 0, v11, vcc
	v_cndmask_b32_e32 v10, 0, v10, vcc
	v_cndmask_b32_e32 v9, 0, v9, vcc
	v_cndmask_b32_e32 v8, 0, v8, vcc
	s_waitcnt vmcnt(0)
	v_cndmask_b32_e32 v15, 0, v15, vcc
	v_cndmask_b32_e32 v14, 0, v14, vcc
	v_cndmask_b32_e32 v13, 0, v13, vcc
	v_cndmask_b32_e32 v12, 0, v12, vcc
	v_add_co_u32_e32 v16, vcc, s58, v16
	s_nop 1
	v_addc_co_u32_e32 v17, vcc, 0, v17, vcc
	global_load_dwordx4 v[16:19], v[16:17], off offset:1536
	s_cselect_b64 vcc, -1, 0
	s_add_i32 s0, s0, s3
	s_waitcnt vmcnt(0)
	v_cndmask_b32_e32 v19, 0, v19, vcc
	v_cndmask_b32_e32 v18, 0, v18, vcc
	v_cndmask_b32_e32 v17, 0, v17, vcc
	v_cndmask_b32_e32 v16, 0, v16, vcc
	v_add_co_u32_e32 v20, vcc, s58, v20
	s_nop 1
	v_addc_co_u32_e32 v21, vcc, 0, v21, vcc
	global_load_dwordx4 v[20:23], v[20:21], off offset:1536
	v_cmp_gt_u32_e32 vcc, s15, v24
	v_add_u32_e32 v24, 12, v56
	v_max_i32_e32 v24, 8, v24
	v_mul_lo_u32 v24, v24, s6
	v_add_u32_e32 v208, 0xffff9000, v24
	v_lshl_add_u64 v[24:25], s[84:85], 0, v[208:209]
	v_lshl_add_u64 v[24:25], v[24:25], 0, v[130:131]
	s_waitcnt vmcnt(0)
	v_cndmask_b32_e32 v23, 0, v23, vcc
	v_cndmask_b32_e32 v22, 0, v22, vcc
	v_cndmask_b32_e32 v21, 0, v21, vcc
	v_cndmask_b32_e32 v20, 0, v20, vcc
	v_add_co_u32_e32 v24, vcc, s58, v24
	s_nop 1
	v_addc_co_u32_e32 v25, vcc, 0, v25, vcc
	global_load_dwordx4 v[24:27], v[24:25], off offset:1536
	v_cmp_gt_u32_e32 vcc, s15, v28
	v_add_u32_e32 v28, 14, v56
	v_max_i32_e32 v28, 8, v28
	v_mul_lo_u32 v28, v28, s6
	v_add_u32_e32 v208, 0xffff9000, v28
	v_lshl_add_u64 v[28:29], s[84:85], 0, v[208:209]
	v_lshl_add_u64 v[28:29], v[28:29], 0, v[130:131]
	s_waitcnt vmcnt(0)
	v_cndmask_b32_e32 v27, 0, v27, vcc
	v_cndmask_b32_e32 v26, 0, v26, vcc
	v_cndmask_b32_e32 v25, 0, v25, vcc
	v_cndmask_b32_e32 v24, 0, v24, vcc
	v_add_co_u32_e32 v28, vcc, s58, v28
	s_nop 1
	v_addc_co_u32_e32 v29, vcc, 0, v29, vcc
	global_load_dwordx4 v[28:31], v[28:29], off offset:1536
	v_cmp_gt_u32_e32 vcc, s15, v32
	v_add_u32_e32 v32, 16, v56
	v_max_i32_e32 v32, 8, v32
	v_mul_lo_u32 v208, v32, s6
	v_lshl_add_u64 v[32:33], s[84:85], 0, v[208:209]
	v_lshl_add_u64 v[32:33], v[32:33], 0, v[130:131]
	s_waitcnt vmcnt(0)
	v_cndmask_b32_e32 v31, 0, v31, vcc
	v_cndmask_b32_e32 v30, 0, v30, vcc
	v_cndmask_b32_e32 v29, 0, v29, vcc
	v_cndmask_b32_e32 v28, 0, v28, vcc
	v_add_co_u32_e32 v32, vcc, s16, v32
	s_nop 1
	v_addc_co_u32_e32 v33, vcc, 0, v33, vcc
	global_load_dwordx4 v[32:35], v[32:33], off offset:1536
	v_cmp_gt_u32_e32 vcc, s15, v36
	v_add_u32_e32 v36, 18, v56
	v_max_i32_e32 v36, 8, v36
	v_mul_lo_u32 v208, v36, s6
	v_lshl_add_u64 v[36:37], s[84:85], 0, v[208:209]
	v_lshl_add_u64 v[36:37], v[36:37], 0, v[130:131]
	s_waitcnt vmcnt(0)
	v_cndmask_b32_e32 v35, 0, v35, vcc
	v_cndmask_b32_e32 v34, 0, v34, vcc
	v_cndmask_b32_e32 v33, 0, v33, vcc
	v_cndmask_b32_e32 v32, 0, v32, vcc
	v_add_co_u32_e32 v36, vcc, s16, v36
	s_nop 1
	v_addc_co_u32_e32 v37, vcc, 0, v37, vcc
	global_load_dwordx4 v[36:39], v[36:37], off offset:1536
	v_cmp_gt_u32_e32 vcc, s15, v40
	v_add_u32_e32 v40, 20, v56
	v_max_i32_e32 v40, 8, v40
	v_mul_lo_u32 v208, v40, s6
	v_lshl_add_u64 v[40:41], s[84:85], 0, v[208:209]
	v_lshl_add_u64 v[40:41], v[40:41], 0, v[130:131]
	s_waitcnt vmcnt(0)
	v_cndmask_b32_e32 v39, 0, v39, vcc
	v_cndmask_b32_e32 v38, 0, v38, vcc
	v_cndmask_b32_e32 v37, 0, v37, vcc
	v_cndmask_b32_e32 v36, 0, v36, vcc
	v_add_co_u32_e32 v40, vcc, s16, v40
	s_nop 1
	v_addc_co_u32_e32 v41, vcc, 0, v41, vcc
	global_load_dwordx4 v[40:43], v[40:41], off offset:1536
	v_cmp_gt_u32_e32 vcc, s15, v44
	v_add_u32_e32 v44, 22, v56
	v_max_i32_e32 v44, 8, v44
	v_mul_lo_u32 v208, v44, s6
	v_lshl_add_u64 v[44:45], s[84:85], 0, v[208:209]
	v_lshl_add_u64 v[44:45], v[44:45], 0, v[130:131]
	s_waitcnt vmcnt(0)
	v_cndmask_b32_e32 v43, 0, v43, vcc
	v_cndmask_b32_e32 v42, 0, v42, vcc
	v_cndmask_b32_e32 v41, 0, v41, vcc
	v_cndmask_b32_e32 v40, 0, v40, vcc
	v_add_co_u32_e32 v44, vcc, s16, v44
	s_nop 1
	v_addc_co_u32_e32 v45, vcc, 0, v45, vcc
	global_load_dwordx4 v[44:47], v[44:45], off offset:1536
	v_cmp_gt_u32_e32 vcc, s15, v48
	v_add_u32_e32 v48, 24, v56
	v_max_i32_e32 v48, 8, v48
	v_add_u32_e32 v48, -8, v48
	v_min_u32_e32 v48, 0xffff, v48
	v_mul_u32_u24_e32 v208, 0xe00, v48
	v_lshl_add_u64 v[48:49], s[84:85], 0, v[208:209]
	v_lshl_add_u64 v[48:49], v[48:49], 0, v[130:131]
	s_waitcnt vmcnt(0)
	v_cndmask_b32_e32 v47, 0, v47, vcc
	v_cndmask_b32_e32 v46, 0, v46, vcc
	v_cndmask_b32_e32 v45, 0, v45, vcc
	v_cndmask_b32_e32 v44, 0, v44, vcc
	v_add_co_u32_e32 v48, vcc, s58, v48
	s_nop 1
	v_addc_co_u32_e32 v49, vcc, 0, v49, vcc
	global_load_dwordx4 v[48:51], v[48:49], off offset:1536
	v_cmp_gt_u32_e32 vcc, s15, v52
	v_add_u32_e32 v52, 26, v56
	v_max_i32_e32 v52, 8, v52
	v_add_u32_e32 v52, -8, v52
	v_min_u32_e32 v52, 0xffff, v52
	v_mul_u32_u24_e32 v208, 0xe00, v52
	v_lshl_add_u64 v[52:53], s[84:85], 0, v[208:209]
	v_lshl_add_u64 v[52:53], v[52:53], 0, v[130:131]
	s_waitcnt vmcnt(0)
	v_cndmask_b32_e32 v51, 0, v51, vcc
	v_cndmask_b32_e32 v50, 0, v50, vcc
	v_cndmask_b32_e32 v49, 0, v49, vcc
	v_cndmask_b32_e32 v48, 0, v48, vcc
	v_add_co_u32_e32 v52, vcc, s58, v52
	s_nop 1
	v_addc_co_u32_e32 v53, vcc, 0, v53, vcc
	global_load_dwordx4 v[52:55], v[52:53], off offset:1536
	v_cmp_gt_u32_e32 vcc, s15, v57
	v_add_u32_e32 v57, 28, v56
	v_max_i32_e32 v57, 8, v57
	v_add_u32_e32 v57, -8, v57
	v_min_u32_e32 v57, 0xffff, v57
	v_mul_u32_u24_e32 v208, 0xe00, v57
	v_lshl_add_u64 v[58:59], s[84:85], 0, v[208:209]
	v_lshl_add_u64 v[58:59], v[58:59], 0, v[130:131]
	v_add_u32_e32 v56, 30, v56
	v_max_i32_e32 v56, 8, v56
	v_add_u32_e32 v56, -8, v56
	v_min_u32_e32 v56, 0xffff, v56
	v_add_u32_e32 v57, s18, v147
	v_mul_u32_u24_e32 v208, 0xe00, v56
	s_waitcnt vmcnt(0)
	v_cndmask_b32_e32 v55, 0, v55, vcc
	v_cndmask_b32_e32 v54, 0, v54, vcc
	v_cndmask_b32_e32 v53, 0, v53, vcc
	v_cndmask_b32_e32 v52, 0, v52, vcc
	v_add_co_u32_e32 v58, vcc, s58, v58
	s_nop 1
	v_addc_co_u32_e32 v59, vcc, 0, v59, vcc
	global_load_dwordx4 v[58:61], v[58:59], off offset:1536
	v_cmp_gt_u32_e32 vcc, s15, v57
	v_lshl_add_u64 v[56:57], s[84:85], 0, v[208:209]
	v_lshl_add_u64 v[56:57], v[56:57], 0, v[130:131]
	s_waitcnt vmcnt(0)
	v_cndmask_b32_e32 v61, 0, v61, vcc
	v_cndmask_b32_e32 v60, 0, v60, vcc
	v_cndmask_b32_e32 v59, 0, v59, vcc
	v_cndmask_b32_e32 v58, 0, v58, vcc
	v_add_co_u32_e32 v56, vcc, s58, v56
	s_nop 1
	v_addc_co_u32_e32 v57, vcc, 0, v57, vcc
	global_load_dwordx4 v[62:65], v[56:57], off offset:1536
	v_add_u32_e32 v56, s18, v148
	v_cmp_gt_u32_e32 vcc, s15, v56
	v_or_b32_e32 v56, s11, v136
	s_waitcnt vmcnt(0)
	v_cndmask_b32_e32 v65, 0, v65, vcc
	v_cndmask_b32_e32 v64, 0, v64, vcc
	v_cndmask_b32_e32 v63, 0, v63, vcc
	v_cndmask_b32_e32 v62, 0, v62, vcc
	ds_write_b128 v150, v[0:3]
	ds_write_b128 v150, v[4:7] offset:1056
	ds_write_b128 v150, v[8:11] offset:2112
	ds_write_b128 v150, v[12:15] offset:3168
	ds_write_b128 v150, v[16:19] offset:4224
	ds_write_b128 v150, v[20:23] offset:5280
	ds_write_b128 v150, v[24:27] offset:6336
	ds_write_b128 v150, v[28:31] offset:7392
	ds_write_b128 v150, v[32:35] offset:8448
	ds_write_b128 v150, v[36:39] offset:9504
	ds_write_b128 v150, v[40:43] offset:10560
	ds_write_b128 v150, v[44:47] offset:11616
	ds_write_b128 v150, v[48:51] offset:12672
	ds_write_b128 v150, v[52:55] offset:13728
	ds_write_b128 v150, v[58:61] offset:14784
	ds_write_b128 v150, v[62:65] offset:15840
	v_add_u32_e32 v0, s9, v136
	v_ashrrev_i32_e32 v1, 31, v0
	v_lshlrev_b64 v[134:135], 11, v[0:1]
	v_max_i32_e32 v0, 1, v56
	v_min_i32_e32 v1, 0x1fff, v56
	v_sub_u32_e32 v0, v1, v0
	v_add_u32_e32 v0, 2, v0
	v_cvt_f32_i32_e32 v0, v0
	s_waitcnt lgkmcnt(0)
	s_add_i32 s9, s9, s17
	s_cmpk_lt_i32 s0, 0x1000
	v_div_scale_f32 v1, s[18:19], v0, v0, 1.0
	v_rcp_f32_e32 v2, v1
	s_nop 0
	v_fma_f32 v3, -v1, v2, 1.0
	v_fmac_f32_e32 v2, v3, v2
	v_div_scale_f32 v3, vcc, 1.0, v0, 1.0
	v_mul_f32_e32 v4, v3, v2
	v_fma_f32 v5, -v1, v4, v3
	v_fmac_f32_e32 v4, v5, v2
	v_fma_f32 v1, -v1, v4, v3
	v_div_fmas_f32 v1, v1, v2, v4
	v_div_fixup_f32 v20, v1, v0, 1.0
	ds_read_b128 v[0:3], v149 offset:3696
	s_waitcnt lgkmcnt(0)
	v_lshlrev_b32_e32 v4, 16, v0
	v_and_b32_e32 v0, 0xffff0000, v0
	v_lshlrev_b32_e32 v5, 16, v1
	v_and_b32_e32 v1, 0xffff0000, v1
	v_lshlrev_b32_e32 v6, 16, v2
	v_and_b32_e32 v2, 0xffff0000, v2
	v_lshlrev_b32_e32 v7, 16, v3
	v_and_b32_e32 v3, 0xffff0000, v3
	v_add_f32_e32 v8, 0, v0
	v_add_f32_e32 v9, 0, v1
	v_add_f32_e32 v10, 0, v2
	v_add_f32_e32 v11, 0, v3
	ds_read_b128 v[0:3], v149 offset:4224
	v_add_f32_e32 v4, 0, v4
	v_add_f32_e32 v5, 0, v5
	v_add_f32_e32 v6, 0, v6
	v_add_f32_e32 v7, 0, v7
	s_waitcnt lgkmcnt(0)
	v_lshlrev_b32_e32 v12, 16, v0
	v_and_b32_e32 v0, 0xffff0000, v0
	v_lshlrev_b32_e32 v13, 16, v1
	v_and_b32_e32 v1, 0xffff0000, v1
	v_lshlrev_b32_e32 v14, 16, v2
	v_and_b32_e32 v2, 0xffff0000, v2
	v_lshlrev_b32_e32 v15, 16, v3
	v_and_b32_e32 v3, 0xffff0000, v3
	v_add_f32_e32 v8, v8, v0
	v_add_f32_e32 v9, v9, v1
	v_add_f32_e32 v10, v10, v2
	v_add_f32_e32 v11, v11, v3
	v_add_f32_e32 v4, v4, v12
	v_add_f32_e32 v5, v5, v13
	v_add_f32_e32 v6, v6, v14
	v_add_f32_e32 v7, v7, v15
	v_fma_f32 v0, v20, v8, -v0
	v_fma_f32 v1, v20, v9, -v1
	v_fma_f32 v2, v20, v10, -v2
	v_fma_f32 v3, v20, v11, -v3
	v_fma_f32 v4, v20, v4, -v12
	v_fma_f32 v5, v20, v5, -v13
	v_fma_f32 v6, v20, v6, -v14
	v_fma_f32 v7, v20, v7, -v15
	v_cvt_pk_bf16_f32 v0, v4, v0
	v_cvt_pk_bf16_f32 v1, v5, v1
	v_cvt_pk_bf16_f32 v2, v6, v2
	v_cvt_pk_bf16_f32 v3, v7, v3
	global_load_dwordx4 v[12:15], v[74:75], off
	global_load_dwordx4 v[4:7], v[72:73], off
	global_load_dwordx4 v[8:11], v[72:73], off offset:2048
	s_waitcnt vmcnt(2)
	v_mfma_f32_16x16x32_bf16 v[16:19], v[12:15], v[0:3], 0
	global_load_dwordx4 v[12:15], v[76:77], off
	s_waitcnt vmcnt(2)
	v_mfma_f32_16x16x32_bf16 v[4:7], v[4:7], v[0:3], 0
	s_waitcnt vmcnt(1)
	v_mfma_f32_16x16x32_bf16 v[8:11], v[8:11], v[0:3], 0
	s_waitcnt vmcnt(0)
	v_mfma_f32_16x16x32_bf16 v[0:3], v[12:15], v[0:3], 0
	ds_read_b128 v[12:15], v149 offset:3760
	s_waitcnt lgkmcnt(0)
	v_lshlrev_b32_e32 v21, 16, v12
	v_and_b32_e32 v12, 0xffff0000, v12
	v_lshlrev_b32_e32 v22, 16, v13
	v_and_b32_e32 v13, 0xffff0000, v13
	v_lshlrev_b32_e32 v23, 16, v14
	v_and_b32_e32 v14, 0xffff0000, v14
	v_lshlrev_b32_e32 v24, 16, v15
	v_and_b32_e32 v15, 0xffff0000, v15
	v_add_f32_e32 v25, 0, v12
	v_add_f32_e32 v26, 0, v13
	v_add_f32_e32 v27, 0, v14
	v_add_f32_e32 v28, 0, v15
	ds_read_b128 v[12:15], v149 offset:4288
	v_add_f32_e32 v21, 0, v21
	v_add_f32_e32 v22, 0, v22
	v_add_f32_e32 v23, 0, v23
	v_add_f32_e32 v24, 0, v24
	s_waitcnt lgkmcnt(0)
	v_lshlrev_b32_e32 v29, 16, v12
	v_and_b32_e32 v12, 0xffff0000, v12
	v_lshlrev_b32_e32 v30, 16, v13
	v_and_b32_e32 v13, 0xffff0000, v13
	v_lshlrev_b32_e32 v31, 16, v14
	v_and_b32_e32 v14, 0xffff0000, v14
	v_lshlrev_b32_e32 v32, 16, v15
	v_and_b32_e32 v15, 0xffff0000, v15
	v_add_f32_e32 v21, v21, v29
	v_add_f32_e32 v25, v25, v12
	v_add_f32_e32 v22, v22, v30
	v_add_f32_e32 v26, v26, v13
	v_add_f32_e32 v23, v23, v31
	v_add_f32_e32 v27, v27, v14
	v_add_f32_e32 v28, v28, v15
	v_add_f32_e32 v24, v24, v32
	v_fma_f32 v21, v20, v21, -v29
	v_fma_f32 v12, v20, v25, -v12
	v_fma_f32 v22, v20, v22, -v30
	v_fma_f32 v13, v20, v26, -v13
	v_fma_f32 v23, v20, v23, -v31
	v_fma_f32 v14, v20, v27, -v14
	v_fma_f32 v15, v20, v28, -v15
	v_fma_f32 v24, v20, v24, -v32
	v_cvt_pk_bf16_f32 v20, v21, v12
	v_cvt_pk_bf16_f32 v21, v22, v13
	v_cvt_pk_bf16_f32 v22, v23, v14
	v_cvt_pk_bf16_f32 v23, v24, v15
	s_waitcnt vmcnt(0)
	v_mfma_f32_16x16x32_bf16 v[12:15], v[166:169], v[20:23], v[4:7]
	s_nop 2
	s_waitcnt vmcnt(0)
	v_mfma_f32_16x16x32_bf16 v[8:11], v[170:173], v[20:23], v[8:11]
	s_waitcnt vmcnt(0)
	v_mfma_f32_16x16x32_bf16 v[4:7], v[174:177], v[20:23], v[16:19]
	s_nop 2
	s_waitcnt vmcnt(0)
	v_mfma_f32_16x16x32_bf16 v[0:3], v[178:181], v[20:23], v[0:3]
	v_max_i32_e32 v16, 2, v56
	v_min_i32_e32 v17, 0x1ffe, v56
	v_sub_u32_e32 v16, v17, v16
	v_add_u32_e32 v16, 4, v16
	v_cvt_f32_i32_e32 v16, v16
	v_div_scale_f32 v17, s[18:19], v16, v16, 1.0
	v_rcp_f32_e32 v18, v17
	s_nop 0
	v_fma_f32 v19, -v17, v18, 1.0
	v_fmac_f32_e32 v18, v19, v18
	v_div_scale_f32 v19, vcc, 1.0, v16, 1.0
	v_mul_f32_e32 v20, v19, v18
	v_fma_f32 v21, -v17, v20, v19
	v_fmac_f32_e32 v20, v21, v18
	v_fma_f32 v17, -v17, v20, v19
	v_div_fmas_f32 v17, v17, v18, v20
	v_div_fixup_f32 v36, v17, v16, 1.0
	ds_read_b128 v[16:19], v149 offset:3296
	s_waitcnt lgkmcnt(0)
	v_lshlrev_b32_e32 v20, 16, v16
	v_and_b32_e32 v16, 0xffff0000, v16
	v_lshlrev_b32_e32 v21, 16, v17
	v_and_b32_e32 v17, 0xffff0000, v17
	v_lshlrev_b32_e32 v22, 16, v18
	v_and_b32_e32 v18, 0xffff0000, v18
	v_lshlrev_b32_e32 v23, 16, v19
	v_and_b32_e32 v19, 0xffff0000, v19
	v_add_f32_e32 v24, 0, v16
	v_add_f32_e32 v25, 0, v17
	v_add_f32_e32 v26, 0, v18
	v_add_f32_e32 v27, 0, v19
	ds_read_b128 v[16:19], v149 offset:3824
	v_add_f32_e32 v20, 0, v20
	v_add_f32_e32 v21, 0, v21
	v_add_f32_e32 v22, 0, v22
	v_add_f32_e32 v23, 0, v23
	s_waitcnt lgkmcnt(0)
	v_lshlrev_b32_e32 v28, 16, v16
	v_and_b32_e32 v16, 0xffff0000, v16
	v_lshlrev_b32_e32 v29, 16, v17
	v_and_b32_e32 v17, 0xffff0000, v17
	v_lshlrev_b32_e32 v30, 16, v18
	v_and_b32_e32 v18, 0xffff0000, v18
	v_lshlrev_b32_e32 v31, 16, v19
	v_and_b32_e32 v19, 0xffff0000, v19
	v_add_f32_e32 v24, v24, v16
	v_add_f32_e32 v25, v25, v17
	v_add_f32_e32 v26, v26, v18
	v_add_f32_e32 v27, v27, v19
	ds_read_b128 v[16:19], v149 offset:4352
	v_add_f32_e32 v20, v20, v28
	v_add_f32_e32 v21, v21, v29
	v_add_f32_e32 v22, v22, v30
	v_add_f32_e32 v23, v23, v31
	s_waitcnt lgkmcnt(0)
	v_lshlrev_b32_e32 v28, 16, v16
	v_and_b32_e32 v29, 0xffff0000, v16
	v_lshlrev_b32_e32 v30, 16, v17
	v_and_b32_e32 v31, 0xffff0000, v17
	v_lshlrev_b32_e32 v32, 16, v18
	v_and_b32_e32 v33, 0xffff0000, v18
	v_lshlrev_b32_e32 v34, 16, v19
	v_and_b32_e32 v35, 0xffff0000, v19
	ds_read_b128 v[16:19], v149 offset:4880
	v_add_f32_e32 v24, v24, v29
	v_add_f32_e32 v25, v25, v31
	v_add_f32_e32 v26, v26, v33
	v_add_f32_e32 v27, v27, v35
	s_waitcnt lgkmcnt(0)
	v_lshlrev_b32_e32 v37, 16, v16
	v_and_b32_e32 v16, 0xffff0000, v16
	v_lshlrev_b32_e32 v38, 16, v17
	v_and_b32_e32 v17, 0xffff0000, v17
	v_lshlrev_b32_e32 v39, 16, v18
	v_and_b32_e32 v18, 0xffff0000, v18
	v_lshlrev_b32_e32 v40, 16, v19
	v_and_b32_e32 v19, 0xffff0000, v19
	v_add_f32_e32 v20, v20, v28
	v_add_f32_e32 v21, v21, v30
	v_add_f32_e32 v22, v22, v32
	v_add_f32_e32 v23, v23, v34
	v_add_f32_e32 v16, v24, v16
	v_add_f32_e32 v17, v25, v17
	v_add_f32_e32 v18, v26, v18
	v_add_f32_e32 v19, v27, v19
	v_add_f32_e32 v20, v20, v37
	v_add_f32_e32 v21, v21, v38
	v_add_f32_e32 v22, v22, v39
	v_add_f32_e32 v23, v23, v40
	v_fma_f32 v16, v36, v16, -v29
	v_fma_f32 v17, v36, v17, -v31
	v_fma_f32 v18, v36, v18, -v33
	v_fma_f32 v19, v36, v19, -v35
	v_fma_f32 v20, v36, v20, -v28
	v_fma_f32 v21, v36, v21, -v30
	v_fma_f32 v22, v36, v22, -v32
	v_fma_f32 v23, v36, v23, -v34
	v_cvt_pk_bf16_f32 v16, v20, v16
	v_cvt_pk_bf16_f32 v17, v21, v17
	v_cvt_pk_bf16_f32 v18, v22, v18
	v_cvt_pk_bf16_f32 v19, v23, v19
	global_load_dwordx4 v[28:31], v[86:87], off
	global_load_dwordx4 v[20:23], v[82:83], off
	global_load_dwordx4 v[24:27], v[84:85], off
	s_waitcnt vmcnt(2)
	v_mfma_f32_16x16x32_bf16 v[32:35], v[28:31], v[16:19], 0
	global_load_dwordx4 v[28:31], v[88:89], off
	s_waitcnt vmcnt(2)
	v_mfma_f32_16x16x32_bf16 v[20:23], v[20:23], v[16:19], 0
	s_waitcnt vmcnt(1)
	v_mfma_f32_16x16x32_bf16 v[24:27], v[24:27], v[16:19], 0
	s_waitcnt vmcnt(0)
	v_mfma_f32_16x16x32_bf16 v[16:19], v[28:31], v[16:19], 0
	ds_read_b128 v[28:31], v149 offset:3360
	s_waitcnt lgkmcnt(0)
	v_lshlrev_b32_e32 v37, 16, v28
	v_and_b32_e32 v28, 0xffff0000, v28
	v_lshlrev_b32_e32 v38, 16, v29
	v_and_b32_e32 v29, 0xffff0000, v29
	v_lshlrev_b32_e32 v39, 16, v30
	v_and_b32_e32 v30, 0xffff0000, v30
	v_lshlrev_b32_e32 v40, 16, v31
	v_and_b32_e32 v31, 0xffff0000, v31
	v_add_f32_e32 v41, 0, v28
	v_add_f32_e32 v42, 0, v29
	v_add_f32_e32 v43, 0, v30
	v_add_f32_e32 v44, 0, v31
	ds_read_b128 v[28:31], v149 offset:3888
	v_add_f32_e32 v37, 0, v37
	v_add_f32_e32 v38, 0, v38
	v_add_f32_e32 v39, 0, v39
	v_add_f32_e32 v40, 0, v40
	s_waitcnt lgkmcnt(0)
	v_lshlrev_b32_e32 v45, 16, v28
	v_and_b32_e32 v28, 0xffff0000, v28
	v_lshlrev_b32_e32 v46, 16, v29
	v_and_b32_e32 v29, 0xffff0000, v29
	v_lshlrev_b32_e32 v47, 16, v30
	v_and_b32_e32 v30, 0xffff0000, v30
	v_lshlrev_b32_e32 v48, 16, v31
	v_and_b32_e32 v31, 0xffff0000, v31
	v_add_f32_e32 v41, v41, v28
	v_add_f32_e32 v42, v42, v29
	v_add_f32_e32 v43, v43, v30
	v_add_f32_e32 v44, v44, v31
	ds_read_b128 v[28:31], v149 offset:4416
	v_add_f32_e32 v37, v37, v45
	v_add_f32_e32 v38, v38, v46
	v_add_f32_e32 v39, v39, v47
	v_add_f32_e32 v40, v40, v48
	s_waitcnt lgkmcnt(0)
	v_lshlrev_b32_e32 v45, 16, v28
	v_and_b32_e32 v46, 0xffff0000, v28
	v_lshlrev_b32_e32 v47, 16, v29
	v_and_b32_e32 v48, 0xffff0000, v29
	v_lshlrev_b32_e32 v49, 16, v30
	v_and_b32_e32 v50, 0xffff0000, v30
	v_lshlrev_b32_e32 v51, 16, v31
	v_and_b32_e32 v52, 0xffff0000, v31
	ds_read_b128 v[28:31], v149 offset:4944
	v_add_f32_e32 v37, v37, v45
	v_add_f32_e32 v41, v41, v46
	v_add_f32_e32 v38, v38, v47
	v_add_f32_e32 v42, v42, v48
	v_add_f32_e32 v39, v39, v49
	v_add_f32_e32 v43, v43, v50
	v_add_f32_e32 v44, v44, v52
	s_waitcnt lgkmcnt(0)
	v_lshlrev_b32_e32 v53, 16, v28
	v_and_b32_e32 v28, 0xffff0000, v28
	v_lshlrev_b32_e32 v54, 16, v29
	v_and_b32_e32 v29, 0xffff0000, v29
	v_lshlrev_b32_e32 v55, 16, v30
	v_and_b32_e32 v30, 0xffff0000, v30
	v_lshlrev_b32_e32 v57, 16, v31
	v_and_b32_e32 v31, 0xffff0000, v31
	v_add_f32_e32 v40, v40, v51
	v_add_f32_e32 v37, v37, v53
	v_add_f32_e32 v28, v41, v28
	v_add_f32_e32 v38, v38, v54
	v_add_f32_e32 v29, v42, v29
	v_add_f32_e32 v39, v39, v55
	v_add_f32_e32 v30, v43, v30
	v_add_f32_e32 v31, v44, v31
	v_add_f32_e32 v40, v40, v57
	v_fma_f32 v37, v36, v37, -v45
	v_fma_f32 v28, v36, v28, -v46
	v_fma_f32 v38, v36, v38, -v47
	v_fma_f32 v29, v36, v29, -v48
	v_fma_f32 v39, v36, v39, -v49
	v_fma_f32 v30, v36, v30, -v50
	v_fma_f32 v31, v36, v31, -v52
	v_fma_f32 v40, v36, v40, -v51
	v_cvt_pk_bf16_f32 v36, v37, v28
	v_cvt_pk_bf16_f32 v37, v38, v29
	v_cvt_pk_bf16_f32 v38, v39, v30
	v_cvt_pk_bf16_f32 v39, v40, v31
	s_waitcnt vmcnt(0)
	v_mfma_f32_16x16x32_bf16 v[28:31], v[182:185], v[36:39], v[20:23]
	s_nop 2
	s_waitcnt vmcnt(0)
	v_mfma_f32_16x16x32_bf16 v[24:27], v[186:189], v[36:39], v[24:27]
	s_waitcnt vmcnt(0)
	v_mfma_f32_16x16x32_bf16 v[20:23], v[190:193], v[36:39], v[32:35]
	s_nop 2
	s_waitcnt vmcnt(0)
	v_mfma_f32_16x16x32_bf16 v[16:19], v[194:197], v[36:39], v[16:19]
	v_max_i32_e32 v32, 4, v56
	v_min_i32_e32 v33, 0x1ffc, v56
	v_sub_u32_e32 v32, v33, v32
	v_add_u32_e32 v32, 8, v32
	v_cvt_f32_i32_e32 v32, v32
	v_div_scale_f32 v33, s[18:19], v32, v32, 1.0
	v_rcp_f32_e32 v34, v33
	s_nop 0
	v_fma_f32 v35, -v33, v34, 1.0
	v_fmac_f32_e32 v34, v35, v34
	v_div_scale_f32 v35, vcc, 1.0, v32, 1.0
	v_mul_f32_e32 v36, v35, v34
	v_fma_f32 v37, -v33, v36, v35
	v_fmac_f32_e32 v36, v37, v34
	v_fma_f32 v33, -v33, v36, v35
	v_div_fmas_f32 v33, v33, v34, v36
	v_div_fixup_f32 v40, v33, v32, 1.0
	ds_read_b128 v[32:35], v149 offset:2368
	s_waitcnt lgkmcnt(0)
	v_lshlrev_b32_e32 v36, 16, v32
	v_and_b32_e32 v32, 0xffff0000, v32
	v_lshlrev_b32_e32 v37, 16, v33
	v_and_b32_e32 v33, 0xffff0000, v33
	v_lshlrev_b32_e32 v38, 16, v34
	v_and_b32_e32 v34, 0xffff0000, v34
	v_lshlrev_b32_e32 v39, 16, v35
	v_and_b32_e32 v35, 0xffff0000, v35
	v_add_f32_e32 v41, 0, v32
	v_add_f32_e32 v42, 0, v33
	v_add_f32_e32 v43, 0, v34
	v_add_f32_e32 v44, 0, v35
	ds_read_b128 v[32:35], v149 offset:2896
	v_add_f32_e32 v36, 0, v36
	v_add_f32_e32 v37, 0, v37
	v_add_f32_e32 v38, 0, v38
	v_add_f32_e32 v39, 0, v39
	s_waitcnt lgkmcnt(0)
	v_lshlrev_b32_e32 v45, 16, v32
	v_and_b32_e32 v32, 0xffff0000, v32
	v_lshlrev_b32_e32 v46, 16, v33
	v_and_b32_e32 v33, 0xffff0000, v33
	v_lshlrev_b32_e32 v47, 16, v34
	v_and_b32_e32 v34, 0xffff0000, v34
	v_lshlrev_b32_e32 v48, 16, v35
	v_and_b32_e32 v35, 0xffff0000, v35
	v_add_f32_e32 v41, v41, v32
	v_add_f32_e32 v42, v42, v33
	v_add_f32_e32 v43, v43, v34
	v_add_f32_e32 v44, v44, v35
	ds_read_b128 v[32:35], v149 offset:3424
	v_add_f32_e32 v36, v36, v45
	v_add_f32_e32 v37, v37, v46
	v_add_f32_e32 v38, v38, v47
	v_add_f32_e32 v39, v39, v48
	s_waitcnt lgkmcnt(0)
	v_lshlrev_b32_e32 v45, 16, v32
	v_and_b32_e32 v32, 0xffff0000, v32
	v_lshlrev_b32_e32 v46, 16, v33
	v_and_b32_e32 v33, 0xffff0000, v33
	v_lshlrev_b32_e32 v47, 16, v34
	v_and_b32_e32 v34, 0xffff0000, v34
	v_lshlrev_b32_e32 v48, 16, v35
	v_and_b32_e32 v35, 0xffff0000, v35
	v_add_f32_e32 v41, v41, v32
	v_add_f32_e32 v42, v42, v33
	v_add_f32_e32 v43, v43, v34
	v_add_f32_e32 v44, v44, v35
	ds_read_b128 v[32:35], v149 offset:3952
	v_add_f32_e32 v36, v36, v45
	v_add_f32_e32 v37, v37, v46
	v_add_f32_e32 v38, v38, v47
	v_add_f32_e32 v39, v39, v48
	s_waitcnt lgkmcnt(0)
	v_lshlrev_b32_e32 v45, 16, v32
	v_lshlrev_b32_e32 v46, 16, v33
	v_lshlrev_b32_e32 v47, 16, v34
	v_lshlrev_b32_e32 v48, 16, v35
	v_add_f32_e32 v45, v36, v45
	v_add_f32_e32 v46, v37, v46
	v_add_f32_e32 v47, v38, v47
	v_add_f32_e32 v48, v39, v48
	ds_read_b128 v[36:39], v149 offset:4480
	v_and_b32_e32 v32, 0xffff0000, v32
	v_and_b32_e32 v33, 0xffff0000, v33
	v_and_b32_e32 v34, 0xffff0000, v34
	v_and_b32_e32 v35, 0xffff0000, v35
	v_add_f32_e32 v41, v41, v32
	v_add_f32_e32 v42, v42, v33
	v_add_f32_e32 v43, v43, v34
	v_add_f32_e32 v44, v44, v35
	s_waitcnt lgkmcnt(0)
	v_lshlrev_b32_e32 v32, 16, v36
	v_and_b32_e32 v33, 0xffff0000, v36
	v_lshlrev_b32_e32 v34, 16, v37
	v_and_b32_e32 v35, 0xffff0000, v37
	v_lshlrev_b32_e32 v36, 16, v38
	v_and_b32_e32 v37, 0xffff0000, v38
	v_lshlrev_b32_e32 v38, 16, v39
	v_and_b32_e32 v39, 0xffff0000, v39
	v_add_f32_e32 v49, v45, v32
	v_add_f32_e32 v50, v42, v35
	v_add_f32_e32 v51, v43, v37
	v_add_f32_e32 v52, v44, v39
	ds_read_b128 v[42:45], v149 offset:5008
	v_add_f32_e32 v41, v41, v33
	v_add_f32_e32 v46, v46, v34
	v_add_f32_e32 v47, v47, v36
	v_add_f32_e32 v48, v48, v38
	s_waitcnt lgkmcnt(0)
	v_lshlrev_b32_e32 v53, 16, v42
	v_and_b32_e32 v42, 0xffff0000, v42
	v_lshlrev_b32_e32 v54, 16, v43
	v_and_b32_e32 v43, 0xffff0000, v43
	v_lshlrev_b32_e32 v55, 16, v44
	v_and_b32_e32 v44, 0xffff0000, v44
	v_lshlrev_b32_e32 v57, 16, v45
	v_and_b32_e32 v45, 0xffff0000, v45
	v_add_f32_e32 v49, v49, v53
	v_add_f32_e32 v53, v41, v42
	v_add_f32_e32 v50, v50, v43
	v_add_f32_e32 v51, v51, v44
	v_add_f32_e32 v52, v52, v45
	ds_read_b128 v[42:45], v149 offset:5536
	v_add_f32_e32 v46, v46, v54
	v_add_f32_e32 v47, v47, v55
	v_add_f32_e32 v48, v48, v57
	s_waitcnt lgkmcnt(0)
	v_lshlrev_b32_e32 v41, 16, v42
	v_and_b32_e32 v42, 0xffff0000, v42
	v_lshlrev_b32_e32 v54, 16, v43
	v_and_b32_e32 v55, 0xffff0000, v43
	v_lshlrev_b32_e32 v57, 16, v44
	v_and_b32_e32 v58, 0xffff0000, v44
	v_lshlrev_b32_e32 v59, 16, v45
	v_and_b32_e32 v60, 0xffff0000, v45
	v_add_f32_e32 v42, v53, v42
	v_add_f32_e32 v43, v46, v54
	v_add_f32_e32 v44, v50, v55
	v_add_f32_e32 v45, v47, v57
	v_add_f32_e32 v46, v51, v58
	v_add_f32_e32 v47, v48, v59
	v_add_f32_e32 v48, v52, v60
	ds_read_b128 v[50:53], v149 offset:6064
	v_add_f32_e32 v41, v49, v41
	s_waitcnt lgkmcnt(0)
	v_lshlrev_b32_e32 v49, 16, v50
	v_and_b32_e32 v50, 0xffff0000, v50
	v_lshlrev_b32_e32 v54, 16, v51
	v_and_b32_e32 v51, 0xffff0000, v51
	v_lshlrev_b32_e32 v55, 16, v52
	v_and_b32_e32 v52, 0xffff0000, v52
	v_lshlrev_b32_e32 v57, 16, v53
	v_and_b32_e32 v53, 0xffff0000, v53
	v_add_f32_e32 v41, v41, v49
	v_add_f32_e32 v42, v42, v50
	v_add_f32_e32 v43, v43, v54
	v_add_f32_e32 v44, v44, v51
	v_add_f32_e32 v45, v45, v55
	v_add_f32_e32 v46, v46, v52
	v_add_f32_e32 v47, v47, v57
	v_add_f32_e32 v48, v48, v53
	v_fma_f32 v32, v40, v41, -v32
	v_fma_f32 v33, v40, v42, -v33
	v_fma_f32 v34, v40, v43, -v34
	v_fma_f32 v35, v40, v44, -v35
	v_fma_f32 v36, v40, v45, -v36
	v_fma_f32 v37, v40, v46, -v37
	v_fma_f32 v38, v40, v47, -v38
	v_fma_f32 v39, v40, v48, -v39
	v_cvt_pk_bf16_f32 v42, v32, v33
	v_cvt_pk_bf16_f32 v43, v34, v35
	v_cvt_pk_bf16_f32 v44, v36, v37
	v_cvt_pk_bf16_f32 v45, v38, v39
	global_load_dwordx4 v[32:35], v[98:99], off
	global_load_dwordx4 v[36:39], v[100:101], off
	global_load_dwordx4 v[46:49], v[102:103], off
	global_load_dwordx4 v[52:55], v[104:105], off
	s_waitcnt vmcnt(3)
	v_mfma_f32_16x16x32_bf16 v[32:35], v[32:35], v[42:45], 0
	s_waitcnt vmcnt(2)
	v_mfma_f32_16x16x32_bf16 v[36:39], v[36:39], v[42:45], 0
	s_waitcnt vmcnt(1)
	v_mfma_f32_16x16x32_bf16 v[48:51], v[46:49], v[42:45], 0
	s_waitcnt vmcnt(0)
	v_mfma_f32_16x16x32_bf16 v[52:55], v[52:55], v[42:45], 0
	ds_read_b128 v[42:45], v149 offset:2432
	s_waitcnt lgkmcnt(0)
	v_lshlrev_b32_e32 v41, 16, v42
	v_and_b32_e32 v42, 0xffff0000, v42
	v_lshlrev_b32_e32 v46, 16, v43
	v_and_b32_e32 v43, 0xffff0000, v43
	v_lshlrev_b32_e32 v47, 16, v44
	v_and_b32_e32 v44, 0xffff0000, v44
	v_lshlrev_b32_e32 v57, 16, v45
	v_and_b32_e32 v45, 0xffff0000, v45
	v_add_f32_e32 v58, 0, v42
	v_add_f32_e32 v59, 0, v43
	v_add_f32_e32 v60, 0, v44
	v_add_f32_e32 v61, 0, v45
	ds_read_b128 v[42:45], v149 offset:2960
	v_add_f32_e32 v41, 0, v41
	v_add_f32_e32 v46, 0, v46
	v_add_f32_e32 v47, 0, v47
	v_add_f32_e32 v57, 0, v57
	s_waitcnt lgkmcnt(0)
	v_lshlrev_b32_e32 v62, 16, v42
	v_and_b32_e32 v42, 0xffff0000, v42
	v_lshlrev_b32_e32 v63, 16, v43
	v_and_b32_e32 v43, 0xffff0000, v43
	v_lshlrev_b32_e32 v64, 16, v44
	v_and_b32_e32 v44, 0xffff0000, v44
	v_lshlrev_b32_e32 v65, 16, v45
	v_and_b32_e32 v45, 0xffff0000, v45
	v_add_f32_e32 v58, v58, v42
	v_add_f32_e32 v59, v59, v43
	v_add_f32_e32 v60, v60, v44
	v_add_f32_e32 v61, v61, v45
	ds_read_b128 v[42:45], v149 offset:3488
	v_add_f32_e32 v41, v41, v62
	v_add_f32_e32 v46, v46, v63
	v_add_f32_e32 v47, v47, v64
	v_add_f32_e32 v57, v57, v65
	s_waitcnt lgkmcnt(0)
	v_lshlrev_b32_e32 v62, 16, v42
	v_and_b32_e32 v42, 0xffff0000, v42
	v_lshlrev_b32_e32 v63, 16, v43
	v_and_b32_e32 v43, 0xffff0000, v43
	v_lshlrev_b32_e32 v64, 16, v44
	v_and_b32_e32 v44, 0xffff0000, v44
	v_lshlrev_b32_e32 v65, 16, v45
	v_and_b32_e32 v45, 0xffff0000, v45
	v_add_f32_e32 v58, v58, v42
	v_add_f32_e32 v59, v59, v43
	v_add_f32_e32 v60, v60, v44
	v_add_f32_e32 v61, v61, v45
	ds_read_b128 v[42:45], v149 offset:4016
	v_add_f32_e32 v41, v41, v62
	v_add_f32_e32 v46, v46, v63
	v_add_f32_e32 v47, v47, v64
	v_add_f32_e32 v57, v57, v65
	s_waitcnt lgkmcnt(0)
	v_lshlrev_b32_e32 v62, 16, v42
	v_and_b32_e32 v42, 0xffff0000, v42
	v_lshlrev_b32_e32 v63, 16, v43
	v_and_b32_e32 v43, 0xffff0000, v43
	v_lshlrev_b32_e32 v64, 16, v44
	v_and_b32_e32 v44, 0xffff0000, v44
	v_lshlrev_b32_e32 v65, 16, v45
	v_and_b32_e32 v45, 0xffff0000, v45
	v_add_f32_e32 v66, v58, v42
	v_add_f32_e32 v67, v59, v43
	v_add_f32_e32 v68, v60, v44
	v_add_f32_e32 v69, v61, v45
	ds_read_b128 v[58:61], v149 offset:4544
	v_add_f32_e32 v62, v41, v62
	v_add_f32_e32 v63, v46, v63
	v_add_f32_e32 v64, v47, v64
	v_add_f32_e32 v65, v57, v65
	s_waitcnt lgkmcnt(0)
	v_lshlrev_b32_e32 v41, 16, v58
	v_and_b32_e32 v42, 0xffff0000, v58
	v_lshlrev_b32_e32 v43, 16, v59
	v_and_b32_e32 v44, 0xffff0000, v59
	v_lshlrev_b32_e32 v45, 16, v60
	v_and_b32_e32 v46, 0xffff0000, v60
	v_lshlrev_b32_e32 v47, 16, v61
	v_and_b32_e32 v57, 0xffff0000, v61
	ds_read_b128 v[58:61], v149 offset:5072
	v_add_f32_e32 v66, v66, v42
	v_add_f32_e32 v67, v67, v44
	v_add_f32_e32 v68, v68, v46
	v_add_f32_e32 v69, v69, v57
	s_waitcnt lgkmcnt(0)
	v_lshlrev_b32_e32 v70, 16, v58
	v_and_b32_e32 v58, 0xffff0000, v58
	v_lshlrev_b32_e32 v71, 16, v59
	v_and_b32_e32 v59, 0xffff0000, v59
	v_lshlrev_b32_e32 v131, 16, v60
	v_and_b32_e32 v60, 0xffff0000, v60
	v_lshlrev_b32_e32 v133, 16, v61
	v_and_b32_e32 v61, 0xffff0000, v61
	v_add_f32_e32 v66, v66, v58
	v_add_f32_e32 v67, v67, v59
	v_add_f32_e32 v68, v68, v60
	v_add_f32_e32 v69, v69, v61
	ds_read_b128 v[58:61], v149 offset:5600
	v_add_f32_e32 v62, v62, v41
	v_add_f32_e32 v63, v63, v43
	v_add_f32_e32 v64, v64, v45
	v_add_f32_e32 v65, v65, v47
	v_add_f32_e32 v62, v62, v70
	v_add_f32_e32 v63, v63, v71
	v_add_f32_e32 v64, v64, v131
	v_add_f32_e32 v65, v65, v133
	s_waitcnt lgkmcnt(0)
	v_lshlrev_b32_e32 v70, 16, v58
	v_and_b32_e32 v71, 0xffff0000, v58
	v_lshlrev_b32_e32 v131, 16, v59
	v_and_b32_e32 v133, 0xffff0000, v59
	v_lshlrev_b32_e32 v151, 16, v60
	v_and_b32_e32 v152, 0xffff0000, v60
	v_lshlrev_b32_e32 v153, 16, v61
	v_and_b32_e32 v154, 0xffff0000, v61
	v_add_f32_e32 v58, v62, v70
	v_add_f32_e32 v59, v66, v71
	v_add_f32_e32 v60, v63, v131
	v_add_f32_e32 v61, v67, v133
	v_add_f32_e32 v62, v64, v151
	v_add_f32_e32 v63, v68, v152
	v_add_f32_e32 v64, v65, v153
	v_add_f32_e32 v65, v69, v154
	ds_read_b128 v[66:69], v149 offset:6128
	s_waitcnt lgkmcnt(0)
	v_lshlrev_b32_e32 v70, 16, v66
	v_and_b32_e32 v66, 0xffff0000, v66
	v_lshlrev_b32_e32 v71, 16, v67
	v_and_b32_e32 v67, 0xffff0000, v67
	v_lshlrev_b32_e32 v131, 16, v68
	v_and_b32_e32 v68, 0xffff0000, v68
	v_lshlrev_b32_e32 v133, 16, v69
	v_and_b32_e32 v69, 0xffff0000, v69
	v_add_f32_e32 v58, v58, v70
	v_add_f32_e32 v59, v59, v66
	v_add_f32_e32 v60, v60, v71
	v_add_f32_e32 v61, v61, v67
	v_add_f32_e32 v62, v62, v131
	v_add_f32_e32 v63, v63, v68
	v_add_f32_e32 v64, v64, v133
	v_add_f32_e32 v65, v65, v69
	v_fma_f32 v41, v40, v58, -v41
	v_fma_f32 v42, v40, v59, -v42
	v_fma_f32 v43, v40, v60, -v43
	v_fma_f32 v44, v40, v61, -v44
	v_fma_f32 v45, v40, v62, -v45
	v_fma_f32 v46, v40, v63, -v46
	v_fma_f32 v47, v40, v64, -v47
	v_fma_f32 v40, v40, v65, -v57
	v_cvt_pk_bf16_f32 v58, v41, v42
	v_cvt_pk_bf16_f32 v59, v43, v44
	v_cvt_pk_bf16_f32 v60, v45, v46
	v_cvt_pk_bf16_f32 v61, v47, v40
	s_waitcnt vmcnt(0)
	v_mfma_f32_16x16x32_bf16 v[44:47], v[198:201], v[58:61], v[32:35]
	s_nop 2
	s_waitcnt vmcnt(0)
	v_mfma_f32_16x16x32_bf16 v[40:43], v[202:205], v[58:61], v[36:39]
	s_waitcnt vmcnt(0)
	v_mfma_f32_16x16x32_bf16 v[36:39], v[214:217], v[58:61], v[48:51]
	s_nop 1
	v_max_i32_e32 v48, 8, v56
	v_min_i32_e32 v49, 0x1ff8, v56
	v_sub_u32_e32 v48, v49, v48
	v_add_u32_e32 v48, 16, v48
	v_cvt_f32_i32_e32 v48, v48
	s_waitcnt vmcnt(0)
	v_mfma_f32_16x16x32_bf16 v[32:35], v[218:221], v[58:61], v[52:55]
	v_div_scale_f32 v49, s[18:19], v48, v48, 1.0
	v_rcp_f32_e32 v50, v49
	s_mov_b64 s[18:19], 0x1a000200
	v_fma_f32 v51, -v49, v50, 1.0
	v_fmac_f32_e32 v50, v51, v50
	v_div_scale_f32 v51, vcc, 1.0, v48, 1.0
	v_mul_f32_e32 v52, v51, v50
	v_fma_f32 v53, -v49, v52, v51
	v_fmac_f32_e32 v52, v53, v50
	v_fma_f32 v49, -v49, v52, v51
	v_div_fmas_f32 v49, v49, v50, v52
	v_div_fixup_f32 v56, v49, v48, 1.0
	ds_read_b128 v[48:51], v149 offset:384
	s_waitcnt lgkmcnt(0)
	v_lshlrev_b32_e32 v52, 16, v48
	v_and_b32_e32 v48, 0xffff0000, v48
	v_lshlrev_b32_e32 v53, 16, v49
	v_and_b32_e32 v49, 0xffff0000, v49
	v_lshlrev_b32_e32 v54, 16, v50
	v_and_b32_e32 v50, 0xffff0000, v50
	v_lshlrev_b32_e32 v55, 16, v51
	v_and_b32_e32 v51, 0xffff0000, v51
	v_add_f32_e32 v57, 0, v48
	v_add_f32_e32 v58, 0, v49
	v_add_f32_e32 v59, 0, v50
	v_add_f32_e32 v60, 0, v51
	ds_read_b128 v[48:51], v149 offset:912
	v_add_f32_e32 v52, 0, v52
	v_add_f32_e32 v53, 0, v53
	v_add_f32_e32 v54, 0, v54
	v_add_f32_e32 v55, 0, v55
	s_waitcnt lgkmcnt(0)
	v_lshlrev_b32_e32 v61, 16, v48
	v_and_b32_e32 v48, 0xffff0000, v48
	v_lshlrev_b32_e32 v62, 16, v49
	v_and_b32_e32 v49, 0xffff0000, v49
	v_lshlrev_b32_e32 v63, 16, v50
	v_and_b32_e32 v50, 0xffff0000, v50
	v_lshlrev_b32_e32 v64, 16, v51
	v_and_b32_e32 v51, 0xffff0000, v51
	v_add_f32_e32 v57, v57, v48
	v_add_f32_e32 v58, v58, v49
	v_add_f32_e32 v59, v59, v50
	v_add_f32_e32 v60, v60, v51
	ds_read_b128 v[48:51], v149 offset:1440
	v_add_f32_e32 v52, v52, v61
	v_add_f32_e32 v53, v53, v62
	v_add_f32_e32 v54, v54, v63
	v_add_f32_e32 v55, v55, v64
	s_waitcnt lgkmcnt(0)
	v_lshlrev_b32_e32 v61, 16, v48
	v_and_b32_e32 v48, 0xffff0000, v48
	v_lshlrev_b32_e32 v62, 16, v49
	v_and_b32_e32 v49, 0xffff0000, v49
	v_lshlrev_b32_e32 v63, 16, v50
	v_and_b32_e32 v50, 0xffff0000, v50
	v_lshlrev_b32_e32 v64, 16, v51
	v_and_b32_e32 v51, 0xffff0000, v51
	v_add_f32_e32 v57, v57, v48
	v_add_f32_e32 v58, v58, v49
	v_add_f32_e32 v59, v59, v50
	v_add_f32_e32 v60, v60, v51
	ds_read_b128 v[48:51], v149 offset:1968
	v_add_f32_e32 v52, v52, v61
	v_add_f32_e32 v53, v53, v62
	v_add_f32_e32 v54, v54, v63
	v_add_f32_e32 v55, v55, v64
	s_waitcnt lgkmcnt(0)
	v_lshlrev_b32_e32 v61, 16, v48
	v_and_b32_e32 v48, 0xffff0000, v48
	v_lshlrev_b32_e32 v62, 16, v49
	v_and_b32_e32 v49, 0xffff0000, v49
	v_lshlrev_b32_e32 v63, 16, v50
	v_and_b32_e32 v50, 0xffff0000, v50
	v_lshlrev_b32_e32 v64, 16, v51
	v_and_b32_e32 v51, 0xffff0000, v51
	v_add_f32_e32 v57, v57, v48
	v_add_f32_e32 v58, v58, v49
	v_add_f32_e32 v59, v59, v50
	v_add_f32_e32 v60, v60, v51
	ds_read_b128 v[48:51], v149 offset:2496
	v_add_f32_e32 v52, v52, v61
	v_add_f32_e32 v53, v53, v62
	v_add_f32_e32 v54, v54, v63
	v_add_f32_e32 v55, v55, v64
	s_waitcnt lgkmcnt(0)
	v_lshlrev_b32_e32 v61, 16, v48
	v_and_b32_e32 v48, 0xffff0000, v48
	v_lshlrev_b32_e32 v62, 16, v49
	v_and_b32_e32 v49, 0xffff0000, v49
	v_lshlrev_b32_e32 v63, 16, v50
	v_and_b32_e32 v50, 0xffff0000, v50
	v_lshlrev_b32_e32 v64, 16, v51
	v_and_b32_e32 v51, 0xffff0000, v51
	v_add_f32_e32 v57, v57, v48
	v_add_f32_e32 v58, v58, v49
	v_add_f32_e32 v59, v59, v50
	v_add_f32_e32 v60, v60, v51
	ds_read_b128 v[48:51], v149 offset:3024
	v_add_f32_e32 v52, v52, v61
	v_add_f32_e32 v53, v53, v62
	v_add_f32_e32 v54, v54, v63
	v_add_f32_e32 v55, v55, v64
	s_waitcnt lgkmcnt(0)
	v_lshlrev_b32_e32 v61, 16, v48
	v_and_b32_e32 v48, 0xffff0000, v48
	v_lshlrev_b32_e32 v62, 16, v49
	v_and_b32_e32 v49, 0xffff0000, v49
	v_lshlrev_b32_e32 v63, 16, v50
	v_and_b32_e32 v50, 0xffff0000, v50
	v_lshlrev_b32_e32 v64, 16, v51
	v_and_b32_e32 v51, 0xffff0000, v51
	v_add_f32_e32 v57, v57, v48
	v_add_f32_e32 v58, v58, v49
	v_add_f32_e32 v59, v59, v50
	v_add_f32_e32 v60, v60, v51
	ds_read_b128 v[48:51], v149 offset:3552
	v_add_f32_e32 v52, v52, v61
	v_add_f32_e32 v53, v53, v62
	v_add_f32_e32 v54, v54, v63
	v_add_f32_e32 v55, v55, v64
	s_waitcnt lgkmcnt(0)
	v_lshlrev_b32_e32 v61, 16, v48
	v_and_b32_e32 v48, 0xffff0000, v48
	v_lshlrev_b32_e32 v62, 16, v49
	v_and_b32_e32 v49, 0xffff0000, v49
	v_lshlrev_b32_e32 v63, 16, v50
	v_and_b32_e32 v50, 0xffff0000, v50
	v_lshlrev_b32_e32 v64, 16, v51
	v_and_b32_e32 v51, 0xffff0000, v51
	v_add_f32_e32 v57, v57, v48
	v_add_f32_e32 v58, v58, v49
	v_add_f32_e32 v59, v59, v50
	v_add_f32_e32 v60, v60, v51
	ds_read_b128 v[48:51], v149 offset:4080
	v_add_f32_e32 v52, v52, v61
	v_add_f32_e32 v53, v53, v62
	v_add_f32_e32 v54, v54, v63
	v_add_f32_e32 v55, v55, v64
	s_waitcnt lgkmcnt(0)
	v_lshlrev_b32_e32 v61, 16, v48
	v_lshlrev_b32_e32 v62, 16, v49
	v_lshlrev_b32_e32 v63, 16, v50
	v_lshlrev_b32_e32 v64, 16, v51
	v_add_f32_e32 v61, v52, v61
	v_add_f32_e32 v62, v53, v62
	v_add_f32_e32 v63, v54, v63
	v_add_f32_e32 v64, v55, v64
	ds_read_b128 v[52:55], v149 offset:4608
	v_and_b32_e32 v48, 0xffff0000, v48
	v_and_b32_e32 v49, 0xffff0000, v49
	v_and_b32_e32 v50, 0xffff0000, v50
	v_and_b32_e32 v51, 0xffff0000, v51
	v_add_f32_e32 v57, v57, v48
	v_add_f32_e32 v58, v58, v49
	v_add_f32_e32 v59, v59, v50
	v_add_f32_e32 v60, v60, v51
	s_waitcnt lgkmcnt(0)
	v_lshlrev_b32_e32 v48, 16, v52
	v_and_b32_e32 v49, 0xffff0000, v52
	v_lshlrev_b32_e32 v50, 16, v53
	v_and_b32_e32 v51, 0xffff0000, v53
	v_lshlrev_b32_e32 v52, 16, v54
	v_and_b32_e32 v53, 0xffff0000, v54
	v_lshlrev_b32_e32 v54, 16, v55
	v_and_b32_e32 v55, 0xffff0000, v55
	v_add_f32_e32 v65, v61, v48
	v_add_f32_e32 v66, v58, v51
	v_add_f32_e32 v67, v59, v53
	v_add_f32_e32 v68, v60, v55
	ds_read_b128 v[58:61], v149 offset:5136
	v_add_f32_e32 v57, v57, v49
	v_add_f32_e32 v62, v62, v50
	v_add_f32_e32 v63, v63, v52
	v_add_f32_e32 v64, v64, v54
	s_waitcnt lgkmcnt(0)
	v_lshlrev_b32_e32 v69, 16, v58
	v_and_b32_e32 v58, 0xffff0000, v58
	v_lshlrev_b32_e32 v70, 16, v59
	v_and_b32_e32 v59, 0xffff0000, v59
	v_lshlrev_b32_e32 v71, 16, v60
	v_and_b32_e32 v60, 0xffff0000, v60
	v_lshlrev_b32_e32 v131, 16, v61
	v_and_b32_e32 v61, 0xffff0000, v61
	v_add_f32_e32 v57, v57, v58
	v_add_f32_e32 v66, v66, v59
	v_add_f32_e32 v67, v67, v60
	v_add_f32_e32 v68, v68, v61
	ds_read_b128 v[58:61], v149 offset:5664
	v_add_f32_e32 v65, v65, v69
	v_add_f32_e32 v62, v62, v70
	v_add_f32_e32 v63, v63, v71
	v_add_f32_e32 v64, v64, v131
	s_waitcnt lgkmcnt(0)
	v_lshlrev_b32_e32 v69, 16, v58
	v_and_b32_e32 v58, 0xffff0000, v58
	v_lshlrev_b32_e32 v70, 16, v59
	v_and_b32_e32 v59, 0xffff0000, v59
	v_lshlrev_b32_e32 v71, 16, v60
	v_and_b32_e32 v60, 0xffff0000, v60
	v_lshlrev_b32_e32 v131, 16, v61
	v_and_b32_e32 v61, 0xffff0000, v61
	v_add_f32_e32 v57, v57, v58
	v_add_f32_e32 v66, v66, v59
	v_add_f32_e32 v67, v67, v60
	v_add_f32_e32 v68, v68, v61
	ds_read_b128 v[58:61], v149 offset:6192
	v_add_f32_e32 v65, v65, v69
	v_add_f32_e32 v62, v62, v70
	v_add_f32_e32 v63, v63, v71
	v_add_f32_e32 v64, v64, v131
	s_waitcnt lgkmcnt(0)
	v_lshlrev_b32_e32 v69, 16, v58
	v_and_b32_e32 v58, 0xffff0000, v58
	v_lshlrev_b32_e32 v70, 16, v59
	v_and_b32_e32 v59, 0xffff0000, v59
	v_lshlrev_b32_e32 v71, 16, v60
	v_and_b32_e32 v60, 0xffff0000, v60
	v_lshlrev_b32_e32 v131, 16, v61
	v_and_b32_e32 v61, 0xffff0000, v61
	v_add_f32_e32 v57, v57, v58
	v_add_f32_e32 v66, v66, v59
	v_add_f32_e32 v67, v67, v60
	v_add_f32_e32 v68, v68, v61
	ds_read_b128 v[58:61], v149 offset:6720
	v_add_f32_e32 v65, v65, v69
	v_add_f32_e32 v62, v62, v70
	v_add_f32_e32 v63, v63, v71
	v_add_f32_e32 v64, v64, v131
	s_waitcnt lgkmcnt(0)
	v_lshlrev_b32_e32 v69, 16, v58
	v_and_b32_e32 v58, 0xffff0000, v58
	v_lshlrev_b32_e32 v70, 16, v59
	v_and_b32_e32 v59, 0xffff0000, v59
	v_lshlrev_b32_e32 v71, 16, v60
	v_and_b32_e32 v60, 0xffff0000, v60
	v_lshlrev_b32_e32 v131, 16, v61
	v_and_b32_e32 v61, 0xffff0000, v61
	v_add_f32_e32 v57, v57, v58
	v_add_f32_e32 v66, v66, v59
	v_add_f32_e32 v67, v67, v60
	v_add_f32_e32 v68, v68, v61
	ds_read_b128 v[58:61], v149 offset:7248
	v_add_f32_e32 v65, v65, v69
	v_add_f32_e32 v62, v62, v70
	v_add_f32_e32 v63, v63, v71
	v_add_f32_e32 v64, v64, v131
	s_waitcnt lgkmcnt(0)
	v_lshlrev_b32_e32 v69, 16, v58
	v_and_b32_e32 v58, 0xffff0000, v58
	v_lshlrev_b32_e32 v70, 16, v59
	v_and_b32_e32 v59, 0xffff0000, v59
	v_lshlrev_b32_e32 v71, 16, v60
	v_and_b32_e32 v60, 0xffff0000, v60
	v_lshlrev_b32_e32 v131, 16, v61
	v_and_b32_e32 v61, 0xffff0000, v61
	v_add_f32_e32 v65, v65, v69
	v_add_f32_e32 v69, v57, v58
	v_add_f32_e32 v66, v66, v59
	v_add_f32_e32 v67, v67, v60
	v_add_f32_e32 v68, v68, v61
	ds_read_b128 v[58:61], v149 offset:7776
	v_add_f32_e32 v63, v63, v71
	v_add_f32_e32 v64, v64, v131
	v_add_f32_e32 v62, v62, v70
	s_waitcnt lgkmcnt(0)
	v_lshlrev_b32_e32 v131, 16, v60
	v_lshlrev_b32_e32 v151, 16, v61
	v_and_b32_e32 v152, 0xffff0000, v61
	v_add_f32_e32 v61, v63, v131
	v_add_f32_e32 v63, v64, v151
	v_add_f32_e32 v64, v68, v152
	ds_read_b128 v[152:155], v149 offset:8304
	v_lshlrev_b32_e32 v57, 16, v58
	v_and_b32_e32 v58, 0xffff0000, v58
	v_lshlrev_b32_e32 v70, 16, v59
	v_and_b32_e32 v71, 0xffff0000, v59
	v_and_b32_e32 v133, 0xffff0000, v60
	v_add_f32_e32 v57, v65, v57
	v_add_f32_e32 v58, v69, v58
	v_add_f32_e32 v59, v62, v70
	v_add_f32_e32 v60, v66, v71
	v_add_f32_e32 v62, v67, v133
	s_waitcnt lgkmcnt(0)
	v_lshlrev_b32_e32 v65, 16, v152
	v_and_b32_e32 v66, 0xffff0000, v152
	v_lshlrev_b32_e32 v67, 16, v153
	v_and_b32_e32 v68, 0xffff0000, v153
	v_lshlrev_b32_e32 v69, 16, v154
	v_and_b32_e32 v70, 0xffff0000, v154
	v_lshlrev_b32_e32 v71, 16, v155
	v_and_b32_e32 v131, 0xffff0000, v155
	v_add_f32_e32 v57, v57, v65
	v_add_f32_e32 v58, v58, v66
	v_add_f32_e32 v59, v59, v67
	v_add_f32_e32 v60, v60, v68
	v_add_f32_e32 v61, v61, v69
	v_add_f32_e32 v62, v62, v70
	v_add_f32_e32 v63, v63, v71
	v_add_f32_e32 v64, v64, v131
	v_fma_f32 v48, v56, v57, -v48
	v_fma_f32 v49, v56, v58, -v49
	v_fma_f32 v50, v56, v59, -v50
	v_fma_f32 v51, v56, v60, -v51
	v_fma_f32 v52, v56, v61, -v52
	v_fma_f32 v53, v56, v62, -v53
	v_fma_f32 v54, v56, v63, -v54
	v_fma_f32 v55, v56, v64, -v55
	v_cvt_pk_bf16_f32 v58, v48, v49
	v_cvt_pk_bf16_f32 v59, v50, v51
	v_cvt_pk_bf16_f32 v60, v52, v53
	v_cvt_pk_bf16_f32 v61, v54, v55
	global_load_dwordx4 v[48:51], v[114:115], off
	global_load_dwordx4 v[52:55], v[116:117], off
	global_load_dwordx4 v[62:65], v[118:119], off
	global_load_dwordx4 v[68:71], v[120:121], off
	s_waitcnt vmcnt(3)
	v_mfma_f32_16x16x32_bf16 v[48:51], v[48:51], v[58:61], 0
	s_waitcnt vmcnt(2)
	v_mfma_f32_16x16x32_bf16 v[52:55], v[52:55], v[58:61], 0
	s_waitcnt vmcnt(1)
	v_mfma_f32_16x16x32_bf16 v[64:67], v[62:65], v[58:61], 0
	s_waitcnt vmcnt(0)
	v_mfma_f32_16x16x32_bf16 v[68:71], v[68:71], v[58:61], 0
	ds_read_b128 v[58:61], v149 offset:448
	s_waitcnt lgkmcnt(0)
	v_lshlrev_b32_e32 v57, 16, v58
	v_and_b32_e32 v58, 0xffff0000, v58
	v_lshlrev_b32_e32 v62, 16, v59
	v_and_b32_e32 v59, 0xffff0000, v59
	v_lshlrev_b32_e32 v63, 16, v60
	v_and_b32_e32 v60, 0xffff0000, v60
	v_lshlrev_b32_e32 v131, 16, v61
	v_and_b32_e32 v61, 0xffff0000, v61
	v_add_f32_e32 v133, 0, v58
	v_add_f32_e32 v151, 0, v59
	v_add_f32_e32 v152, 0, v60
	v_add_f32_e32 v153, 0, v61
	ds_read_b128 v[58:61], v149 offset:976
	v_add_f32_e32 v57, 0, v57
	v_add_f32_e32 v62, 0, v62
	v_add_f32_e32 v63, 0, v63
	v_add_f32_e32 v131, 0, v131
	s_waitcnt lgkmcnt(0)
	v_lshlrev_b32_e32 v154, 16, v58
	v_and_b32_e32 v58, 0xffff0000, v58
	v_lshlrev_b32_e32 v155, 16, v59
	v_and_b32_e32 v59, 0xffff0000, v59
	v_lshlrev_b32_e32 v156, 16, v60
	v_and_b32_e32 v60, 0xffff0000, v60
	v_lshlrev_b32_e32 v157, 16, v61
	v_and_b32_e32 v61, 0xffff0000, v61
	v_add_f32_e32 v133, v133, v58
	v_add_f32_e32 v151, v151, v59
	v_add_f32_e32 v152, v152, v60
	v_add_f32_e32 v153, v153, v61
	ds_read_b128 v[58:61], v149 offset:1504
	v_add_f32_e32 v57, v57, v154
	v_add_f32_e32 v62, v62, v155
	v_add_f32_e32 v63, v63, v156
	v_add_f32_e32 v131, v131, v157
	s_waitcnt lgkmcnt(0)
	v_lshlrev_b32_e32 v154, 16, v58
	v_and_b32_e32 v58, 0xffff0000, v58
	v_lshlrev_b32_e32 v155, 16, v59
	v_and_b32_e32 v59, 0xffff0000, v59
	v_lshlrev_b32_e32 v156, 16, v60
	v_and_b32_e32 v60, 0xffff0000, v60
	v_lshlrev_b32_e32 v157, 16, v61
	v_and_b32_e32 v61, 0xffff0000, v61
	v_add_f32_e32 v133, v133, v58
	v_add_f32_e32 v151, v151, v59
	v_add_f32_e32 v152, v152, v60
	v_add_f32_e32 v153, v153, v61
	ds_read_b128 v[58:61], v149 offset:2032
	v_add_f32_e32 v57, v57, v154
	v_add_f32_e32 v62, v62, v155
	v_add_f32_e32 v63, v63, v156
	v_add_f32_e32 v131, v131, v157
	s_waitcnt lgkmcnt(0)
	v_lshlrev_b32_e32 v154, 16, v58
	v_and_b32_e32 v58, 0xffff0000, v58
	v_lshlrev_b32_e32 v155, 16, v59
	v_and_b32_e32 v59, 0xffff0000, v59
	v_lshlrev_b32_e32 v156, 16, v60
	v_and_b32_e32 v60, 0xffff0000, v60
	v_lshlrev_b32_e32 v157, 16, v61
	v_and_b32_e32 v61, 0xffff0000, v61
	v_add_f32_e32 v133, v133, v58
	v_add_f32_e32 v151, v151, v59
	v_add_f32_e32 v152, v152, v60
	v_add_f32_e32 v153, v153, v61
	ds_read_b128 v[58:61], v149 offset:2560
	v_add_f32_e32 v57, v57, v154
	v_add_f32_e32 v62, v62, v155
	v_add_f32_e32 v63, v63, v156
	v_add_f32_e32 v131, v131, v157
	s_waitcnt lgkmcnt(0)
	v_lshlrev_b32_e32 v154, 16, v58
	v_and_b32_e32 v58, 0xffff0000, v58
	v_lshlrev_b32_e32 v155, 16, v59
	v_and_b32_e32 v59, 0xffff0000, v59
	v_lshlrev_b32_e32 v156, 16, v60
	v_and_b32_e32 v60, 0xffff0000, v60
	v_lshlrev_b32_e32 v157, 16, v61
	v_and_b32_e32 v61, 0xffff0000, v61
	v_add_f32_e32 v133, v133, v58
	v_add_f32_e32 v151, v151, v59
	v_add_f32_e32 v152, v152, v60
	v_add_f32_e32 v153, v153, v61
	ds_read_b128 v[58:61], v149 offset:3088
	v_add_f32_e32 v57, v57, v154
	v_add_f32_e32 v62, v62, v155
	v_add_f32_e32 v63, v63, v156
	v_add_f32_e32 v131, v131, v157
	s_waitcnt lgkmcnt(0)
	v_lshlrev_b32_e32 v154, 16, v58
	v_and_b32_e32 v58, 0xffff0000, v58
	v_lshlrev_b32_e32 v155, 16, v59
	v_and_b32_e32 v59, 0xffff0000, v59
	v_lshlrev_b32_e32 v156, 16, v60
	v_and_b32_e32 v60, 0xffff0000, v60
	v_lshlrev_b32_e32 v157, 16, v61
	v_and_b32_e32 v61, 0xffff0000, v61
	v_add_f32_e32 v133, v133, v58
	v_add_f32_e32 v151, v151, v59
	v_add_f32_e32 v152, v152, v60
	v_add_f32_e32 v153, v153, v61
	ds_read_b128 v[58:61], v149 offset:3616
	v_add_f32_e32 v57, v57, v154
	v_add_f32_e32 v62, v62, v155
	v_add_f32_e32 v63, v63, v156
	v_add_f32_e32 v131, v131, v157
	s_waitcnt lgkmcnt(0)
	v_lshlrev_b32_e32 v154, 16, v58
	v_and_b32_e32 v58, 0xffff0000, v58
	v_lshlrev_b32_e32 v155, 16, v59
	v_and_b32_e32 v59, 0xffff0000, v59
	v_lshlrev_b32_e32 v156, 16, v60
	v_and_b32_e32 v60, 0xffff0000, v60
	v_lshlrev_b32_e32 v157, 16, v61
	v_and_b32_e32 v61, 0xffff0000, v61
	v_add_f32_e32 v133, v133, v58
	v_add_f32_e32 v151, v151, v59
	v_add_f32_e32 v152, v152, v60
	v_add_f32_e32 v153, v153, v61
	ds_read_b128 v[58:61], v149 offset:4144
	v_add_f32_e32 v57, v57, v154
	v_add_f32_e32 v62, v62, v155
	v_add_f32_e32 v63, v63, v156
	v_add_f32_e32 v131, v131, v157
	s_waitcnt lgkmcnt(0)
	v_lshlrev_b32_e32 v154, 16, v58
	v_lshlrev_b32_e32 v155, 16, v59
	v_lshlrev_b32_e32 v156, 16, v60
	v_and_b32_e32 v60, 0xffff0000, v60
	v_lshlrev_b32_e32 v157, 16, v61
	v_and_b32_e32 v61, 0xffff0000, v61
	v_add_f32_e32 v158, v57, v154
	v_add_f32_e32 v159, v62, v155
	v_add_f32_e32 v160, v152, v60
	v_add_f32_e32 v161, v153, v61
	ds_read_b128 v[152:155], v149 offset:4672
	v_and_b32_e32 v58, 0xffff0000, v58
	v_and_b32_e32 v59, 0xffff0000, v59
	v_add_f32_e32 v133, v133, v58
	v_add_f32_e32 v151, v151, v59
	v_add_f32_e32 v156, v63, v156
	v_add_f32_e32 v157, v131, v157
	s_waitcnt lgkmcnt(0)
	v_lshlrev_b32_e32 v57, 16, v152
	v_and_b32_e32 v58, 0xffff0000, v152
	v_lshlrev_b32_e32 v59, 16, v153
	v_and_b32_e32 v60, 0xffff0000, v153
	v_lshlrev_b32_e32 v61, 16, v154
	v_and_b32_e32 v62, 0xffff0000, v154
	v_lshlrev_b32_e32 v63, 16, v155
	v_and_b32_e32 v131, 0xffff0000, v155
	ds_read_b128 v[152:155], v149 offset:5200
	v_add_f32_e32 v133, v133, v58
	v_add_f32_e32 v151, v151, v60
	v_add_f32_e32 v160, v160, v62
	v_add_f32_e32 v161, v161, v131
	s_waitcnt lgkmcnt(0)
	v_lshlrev_b32_e32 v162, 16, v152
	v_and_b32_e32 v152, 0xffff0000, v152
	v_lshlrev_b32_e32 v163, 16, v153
	v_and_b32_e32 v153, 0xffff0000, v153
	v_lshlrev_b32_e32 v164, 16, v154
	v_and_b32_e32 v154, 0xffff0000, v154
	v_lshlrev_b32_e32 v165, 16, v155
	v_and_b32_e32 v155, 0xffff0000, v155
	v_add_f32_e32 v133, v133, v152
	v_add_f32_e32 v151, v151, v153
	v_add_f32_e32 v160, v160, v154
	v_add_f32_e32 v161, v161, v155
	ds_read_b128 v[152:155], v149 offset:5728
	v_add_f32_e32 v158, v158, v57
	v_add_f32_e32 v159, v159, v59
	v_add_f32_e32 v156, v156, v61
	v_add_f32_e32 v157, v157, v63
	v_add_f32_e32 v158, v158, v162
	v_add_f32_e32 v159, v159, v163
	v_add_f32_e32 v156, v156, v164
	v_add_f32_e32 v157, v157, v165
	s_waitcnt lgkmcnt(0)
	v_lshlrev_b32_e32 v162, 16, v152
	v_and_b32_e32 v152, 0xffff0000, v152
	v_lshlrev_b32_e32 v163, 16, v153
	v_and_b32_e32 v153, 0xffff0000, v153
	v_lshlrev_b32_e32 v164, 16, v154
	v_and_b32_e32 v154, 0xffff0000, v154
	v_lshlrev_b32_e32 v165, 16, v155
	v_and_b32_e32 v155, 0xffff0000, v155
	v_add_f32_e32 v133, v133, v152
	v_add_f32_e32 v151, v151, v153
	v_add_f32_e32 v160, v160, v154
	v_add_f32_e32 v161, v161, v155
	ds_read_b128 v[152:155], v149 offset:6256
	v_add_f32_e32 v158, v158, v162
	v_add_f32_e32 v159, v159, v163
	v_add_f32_e32 v156, v156, v164
	v_add_f32_e32 v157, v157, v165
	s_waitcnt lgkmcnt(0)
	v_lshlrev_b32_e32 v162, 16, v152
	v_and_b32_e32 v152, 0xffff0000, v152
	v_lshlrev_b32_e32 v163, 16, v153
	v_and_b32_e32 v153, 0xffff0000, v153
	v_lshlrev_b32_e32 v164, 16, v154
	v_and_b32_e32 v154, 0xffff0000, v154
	v_lshlrev_b32_e32 v165, 16, v155
	v_and_b32_e32 v155, 0xffff0000, v155
	v_add_f32_e32 v133, v133, v152
	v_add_f32_e32 v151, v151, v153
	v_add_f32_e32 v160, v160, v154
	v_add_f32_e32 v161, v161, v155
	ds_read_b128 v[152:155], v149 offset:6784
	v_add_f32_e32 v158, v158, v162
	v_add_f32_e32 v159, v159, v163
	v_add_f32_e32 v156, v156, v164
	v_add_f32_e32 v157, v157, v165
	s_waitcnt lgkmcnt(0)
	v_lshlrev_b32_e32 v162, 16, v152
	v_and_b32_e32 v152, 0xffff0000, v152
	v_lshlrev_b32_e32 v163, 16, v153
	v_and_b32_e32 v153, 0xffff0000, v153
	v_lshlrev_b32_e32 v164, 16, v154
	v_and_b32_e32 v154, 0xffff0000, v154
	v_lshlrev_b32_e32 v165, 16, v155
	v_and_b32_e32 v155, 0xffff0000, v155
	v_add_f32_e32 v133, v133, v152
	v_add_f32_e32 v151, v151, v153
	v_add_f32_e32 v160, v160, v154
	v_add_f32_e32 v161, v161, v155
	ds_read_b128 v[152:155], v149 offset:7312
	v_add_f32_e32 v158, v158, v162
	v_add_f32_e32 v159, v159, v163
	v_add_f32_e32 v156, v156, v164
	v_add_f32_e32 v157, v157, v165
	s_waitcnt lgkmcnt(0)
	v_lshlrev_b32_e32 v162, 16, v152
	v_and_b32_e32 v152, 0xffff0000, v152
	v_lshlrev_b32_e32 v163, 16, v153
	v_and_b32_e32 v153, 0xffff0000, v153
	v_lshlrev_b32_e32 v164, 16, v154
	v_and_b32_e32 v154, 0xffff0000, v154
	v_lshlrev_b32_e32 v165, 16, v155
	v_and_b32_e32 v155, 0xffff0000, v155
	v_add_f32_e32 v133, v133, v152
	v_add_f32_e32 v151, v151, v153
	v_add_f32_e32 v160, v160, v154
	v_add_f32_e32 v161, v161, v155
	ds_read_b128 v[152:155], v149 offset:7840
	v_add_f32_e32 v158, v158, v162
	v_add_f32_e32 v159, v159, v163
	v_add_f32_e32 v156, v156, v164
	v_add_f32_e32 v157, v157, v165
	s_waitcnt lgkmcnt(0)
	v_lshlrev_b32_e32 v162, 16, v152
	v_and_b32_e32 v152, 0xffff0000, v152
	v_lshlrev_b32_e32 v163, 16, v153
	v_and_b32_e32 v153, 0xffff0000, v153
	v_lshlrev_b32_e32 v164, 16, v154
	v_and_b32_e32 v154, 0xffff0000, v154
	v_lshlrev_b32_e32 v165, 16, v155
	v_and_b32_e32 v155, 0xffff0000, v155
	v_add_f32_e32 v133, v133, v152
	v_add_f32_e32 v151, v151, v153
	v_add_f32_e32 v160, v160, v154
	v_add_f32_e32 v161, v161, v155
	ds_read_b128 v[152:155], v149 offset:8368
	v_add_f32_e32 v158, v158, v162
	v_add_f32_e32 v159, v159, v163
	v_add_f32_e32 v156, v156, v164
	v_add_f32_e32 v157, v157, v165
	s_waitcnt lgkmcnt(0)
	v_lshlrev_b32_e32 v162, 16, v152
	v_and_b32_e32 v152, 0xffff0000, v152
	v_lshlrev_b32_e32 v163, 16, v153
	v_and_b32_e32 v153, 0xffff0000, v153
	v_lshlrev_b32_e32 v164, 16, v154
	v_and_b32_e32 v154, 0xffff0000, v154
	v_lshlrev_b32_e32 v165, 16, v155
	v_and_b32_e32 v155, 0xffff0000, v155
	v_add_f32_e32 v158, v158, v162
	v_add_f32_e32 v133, v133, v152
	v_add_f32_e32 v152, v159, v163
	v_add_f32_e32 v151, v151, v153
	v_add_f32_e32 v153, v156, v164
	v_add_f32_e32 v154, v160, v154
	v_add_f32_e32 v156, v157, v165
	v_add_f32_e32 v155, v161, v155
	v_fma_f32 v57, v56, v158, -v57
	v_fma_f32 v58, v56, v133, -v58
	v_fma_f32 v59, v56, v152, -v59
	v_fma_f32 v60, v56, v151, -v60
	v_fma_f32 v61, v56, v153, -v61
	v_fma_f32 v62, v56, v154, -v62
	v_fma_f32 v63, v56, v156, -v63
	v_fma_f32 v56, v56, v155, -v131
	v_cvt_pk_bf16_f32 v152, v57, v58
	v_cvt_pk_bf16_f32 v153, v59, v60
	v_cvt_pk_bf16_f32 v154, v61, v62
	v_cvt_pk_bf16_f32 v155, v63, v56
	s_waitcnt vmcnt(0)
	v_mfma_f32_16x16x32_bf16 v[60:63], v[222:225], v[152:155], v[48:51]
	s_nop 2
	v_mov_b32_e32 v133, v209
	s_waitcnt vmcnt(0)
	v_mfma_f32_16x16x32_bf16 v[56:59], v[226:229], v[152:155], v[52:55]
	s_waitcnt vmcnt(0)
	v_mfma_f32_16x16x32_bf16 v[52:55], v[230:233], v[152:155], v[64:67]
	s_nop 1
	v_pk_mul_f32 v[64:65], v[14:15], v[14:15]
	v_pk_mul_f32 v[66:67], v[12:13], v[12:13]
	s_waitcnt vmcnt(0)
	v_mfma_f32_16x16x32_bf16 v[48:51], v[234:237], v[152:155], v[68:71]
	s_nop 2
	v_pk_mov_b32 v[68:69], v[66:67], v[64:65] op_sel:[1,0]
	v_mov_b32_e32 v67, v65
	v_pk_add_f32 v[64:65], v[68:69], v[66:67]
	v_pk_mul_f32 v[66:67], v[10:11], v[10:11]
	v_pk_mul_f32 v[68:69], v[8:9], v[8:9]
	v_pk_add_f32 v[64:65], v[64:65], v[64:65] op_sel:[0,1] op_sel_hi:[1,0]
	v_pk_mov_b32 v[70:71], v[68:69], v[66:67] op_sel:[1,0]
	v_mov_b32_e32 v69, v67
	v_pk_add_f32 v[66:67], v[70:71], v[68:69]
	v_mul_f32_e32 v68, v0, v0
	v_mul_f32_e32 v69, v1, v1
	v_pk_add_f32 v[66:67], v[66:67], v[66:67] op_sel:[0,1] op_sel_hi:[1,0]
	v_mov_b32_e32 v65, v68
	v_mov_b32_e32 v67, v69
	v_pk_add_f32 v[64:65], v[64:65], v[66:67]
	v_mul_f32_e32 v66, v5, v5
	v_mul_f32_e32 v68, v7, v7
	v_mul_f32_e32 v70, v2, v2
	v_mul_f32_e32 v71, v3, v3
	v_pk_fma_f32 v[66:67], v[4:5], v[4:5], v[66:67] op_sel_hi:[1,1,0]
	v_pk_fma_f32 v[68:69], v[6:7], v[6:7], v[68:69] op_sel_hi:[1,1,0]
	v_mov_b32_e32 v67, v70
	v_mov_b32_e32 v69, v71
	v_pk_add_f32 v[66:67], v[66:67], v[68:69]
	v_pk_mul_f32 v[68:69], v[28:29], v[28:29]
	v_pk_add_f32 v[64:65], v[64:65], v[66:67]
	v_pk_mul_f32 v[66:67], v[30:31], v[30:31]
	v_pk_add_f32 v[64:65], v[64:65], v[64:65] op_sel:[0,1] op_sel_hi:[1,0]
	v_pk_mov_b32 v[70:71], v[68:69], v[66:67] op_sel:[1,0]
	v_mov_b32_e32 v69, v67
	v_pk_add_f32 v[66:67], v[70:71], v[68:69]
	v_mul_f32_e32 v68, v20, v20
	v_mul_f32_e32 v69, v21, v21
	v_pk_add_f32 v[66:67], v[66:67], v[66:67] op_sel:[0,1] op_sel_hi:[1,0]
	v_mov_b32_e32 v65, v68
	v_mov_b32_e32 v67, v69
	v_pk_add_f32 v[64:65], v[64:65], v[66:67]
	v_mul_f32_e32 v66, v25, v25
	v_mul_f32_e32 v68, v27, v27
	v_mul_f32_e32 v70, v22, v22
	v_mul_f32_e32 v71, v23, v23
	v_pk_fma_f32 v[66:67], v[24:25], v[24:25], v[66:67] op_sel_hi:[1,1,0]
	v_pk_fma_f32 v[68:69], v[26:27], v[26:27], v[68:69] op_sel_hi:[1,1,0]
	v_mov_b32_e32 v67, v70
	v_mov_b32_e32 v69, v71
	v_pk_add_f32 v[66:67], v[66:67], v[68:69]
	v_pk_mul_f32 v[68:69], v[16:17], v[16:17]
	v_pk_add_f32 v[64:65], v[64:65], v[66:67]
	v_pk_mul_f32 v[66:67], v[18:19], v[18:19]
	v_pk_add_f32 v[64:65], v[64:65], v[64:65] op_sel:[0,1] op_sel_hi:[1,0]
	v_pk_mov_b32 v[70:71], v[68:69], v[66:67] op_sel:[1,0]
	v_mov_b32_e32 v69, v67
	v_pk_add_f32 v[66:67], v[70:71], v[68:69]
	v_mul_f32_e32 v68, v40, v40
	v_mul_f32_e32 v69, v41, v41
	v_pk_add_f32 v[66:67], v[66:67], v[66:67] op_sel:[0,1] op_sel_hi:[1,0]
	v_mov_b32_e32 v65, v68
	v_mov_b32_e32 v67, v69
	v_pk_add_f32 v[64:65], v[64:65], v[66:67]
	v_mul_f32_e32 v66, v45, v45
	v_mul_f32_e32 v68, v47, v47
	v_mul_f32_e32 v70, v42, v42
	v_mul_f32_e32 v71, v43, v43
	v_pk_fma_f32 v[66:67], v[44:45], v[44:45], v[66:67] op_sel_hi:[1,1,0]
	v_pk_fma_f32 v[68:69], v[46:47], v[46:47], v[68:69] op_sel_hi:[1,1,0]
	v_mov_b32_e32 v67, v70
	v_mov_b32_e32 v69, v71
	v_pk_add_f32 v[66:67], v[66:67], v[68:69]
	v_pk_mul_f32 v[68:69], v[36:37], v[36:37]
	v_pk_add_f32 v[64:65], v[64:65], v[66:67]
	v_pk_mul_f32 v[66:67], v[38:39], v[38:39]
	v_pk_add_f32 v[64:65], v[64:65], v[64:65] op_sel:[0,1] op_sel_hi:[1,0]
	v_pk_mov_b32 v[70:71], v[68:69], v[66:67] op_sel:[1,0]
	v_mov_b32_e32 v69, v67
	v_pk_add_f32 v[66:67], v[70:71], v[68:69]
	v_mul_f32_e32 v68, v60, v60
	v_mul_f32_e32 v69, v61, v61
	v_pk_add_f32 v[66:67], v[66:67], v[66:67] op_sel:[0,1] op_sel_hi:[1,0]
	v_mov_b32_e32 v65, v68
	v_mov_b32_e32 v67, v69
	v_pk_add_f32 v[64:65], v[64:65], v[66:67]
	v_mul_f32_e32 v66, v33, v33
	v_mul_f32_e32 v68, v35, v35
	v_mul_f32_e32 v70, v62, v62
	v_mul_f32_e32 v71, v63, v63
	v_pk_fma_f32 v[66:67], v[32:33], v[32:33], v[66:67] op_sel_hi:[1,1,0]
	v_pk_fma_f32 v[68:69], v[34:35], v[34:35], v[68:69] op_sel_hi:[1,1,0]
	v_mov_b32_e32 v67, v70
	v_mov_b32_e32 v69, v71
	v_pk_add_f32 v[66:67], v[66:67], v[68:69]
	v_pk_mul_f32 v[68:69], v[56:57], v[56:57]
	v_pk_add_f32 v[64:65], v[64:65], v[66:67]
	v_pk_mul_f32 v[66:67], v[58:59], v[58:59]
	v_pk_add_f32 v[64:65], v[64:65], v[64:65] op_sel:[0,1] op_sel_hi:[1,0]
	v_pk_mov_b32 v[70:71], v[68:69], v[66:67] op_sel:[1,0]
	v_mov_b32_e32 v69, v67
	v_pk_add_f32 v[66:67], v[70:71], v[68:69]
	v_mul_f32_e32 v68, v48, v48
	v_mul_f32_e32 v69, v49, v49
	v_pk_add_f32 v[66:67], v[66:67], v[66:67] op_sel:[0,1] op_sel_hi:[1,0]
	v_mov_b32_e32 v65, v68
	v_mov_b32_e32 v67, v69
	v_pk_add_f32 v[64:65], v[64:65], v[66:67]
	v_mul_f32_e32 v66, v53, v53
	v_mul_f32_e32 v68, v55, v55
	v_mul_f32_e32 v70, v50, v50
	v_mul_f32_e32 v71, v51, v51
	v_pk_fma_f32 v[66:67], v[52:53], v[52:53], v[66:67] op_sel_hi:[1,1,0]
	v_pk_fma_f32 v[68:69], v[54:55], v[54:55], v[68:69] op_sel_hi:[1,1,0]
	v_mov_b32_e32 v67, v70
	v_mov_b32_e32 v69, v71
	v_pk_add_f32 v[66:67], v[66:67], v[68:69]
	v_and_b32_e32 v68, 64, v245
	v_pk_add_f32 v[64:65], v[64:65], v[66:67]
	v_xor_b32_e32 v67, 16, v245
	v_add_u32_e32 v68, 64, v68
	v_cmp_lt_i32_e32 vcc, v67, v68
	v_add_f32_e32 v66, v64, v65
	v_lshl_add_u64 v[64:65], s[84:85], 0, v[134:135]
	v_cndmask_b32_e32 v67, v245, v67, vcc
	v_lshlrev_b32_e32 v67, 2, v67
	ds_bpermute_b32 v67, v67, v66
	v_lshl_add_u64 v[64:65], v[64:65], 0, v[132:133]
	s_waitcnt lgkmcnt(0)
	v_add_f32_e32 v66, v66, v67
	v_xor_b32_e32 v67, 32, v245
	v_cmp_lt_i32_e32 vcc, v67, v68
	v_lshl_add_u64 v[68:69], v[64:65], 0, s[18:19]
	s_nop 0
	v_cndmask_b32_e32 v67, v245, v67, vcc
	v_lshlrev_b32_e32 v67, 2, v67
	ds_bpermute_b32 v67, v67, v66
	s_waitcnt lgkmcnt(0)
	v_add_f32_e32 v66, v66, v67
	v_fmamk_f32 v66, v66, 0x3b800000, v244
	v_cmp_gt_f32_e32 vcc, s7, v66
	v_mul_f32_e32 v67, 0x4b800000, v66
	s_nop 0
	v_cndmask_b32_e32 v66, v66, v67, vcc
	v_rsq_f32_e32 v66, v66
	s_nop 0
	v_mul_f32_e32 v67, 0x45800000, v66
	v_cndmask_b32_e32 v66, v66, v67, vcc
	v_mul_f32_e32 v12, v12, v66
	v_mul_f32_e32 v13, v13, v66
	v_cvt_pk_bf16_f32 v12, v12, v13
	v_mul_f32_e32 v13, v14, v66
	v_mul_f32_e32 v14, v15, v66
	v_cvt_pk_bf16_f32 v13, v13, v14
	v_add_co_u32_e32 v14, vcc, s47, v64
	v_mul_f32_e32 v8, v8, v66
	s_nop 0
	v_addc_co_u32_e32 v15, vcc, 0, v65, vcc
	v_mul_f32_e32 v9, v9, v66
	global_store_dwordx2 v[14:15], v[12:13], off offset:512
	v_cvt_pk_bf16_f32 v8, v8, v9
	v_mul_f32_e32 v9, v10, v66
	v_mul_f32_e32 v4, v4, v66
	v_mul_f32_e32 v5, v5, v66
	v_mul_f32_e32 v10, v11, v66
	v_cvt_pk_bf16_f32 v9, v9, v10
	global_store_dwordx2 v[68:69], v[8:9], off offset:32
	v_cvt_pk_bf16_f32 v4, v4, v5
	v_mul_f32_e32 v5, v6, v66
	v_mul_f32_e32 v0, v0, v66
	v_mul_f32_e32 v1, v1, v66
	v_mul_f32_e32 v6, v7, v66
	v_cvt_pk_bf16_f32 v5, v5, v6
	global_store_dwordx2 v[68:69], v[4:5], off offset:64
	v_cvt_pk_bf16_f32 v0, v0, v1
	v_mul_f32_e32 v1, v2, v66
	v_mul_f32_e32 v2, v3, v66
	v_cvt_pk_bf16_f32 v1, v1, v2
	global_store_dwordx2 v[68:69], v[0:1], off offset:96
	v_mul_f32_e32 v0, v28, v66
	v_mul_f32_e32 v1, v29, v66
	v_cvt_pk_bf16_f32 v0, v0, v1
	v_mul_f32_e32 v1, v30, v66
	v_mul_f32_e32 v2, v31, v66
	v_cvt_pk_bf16_f32 v1, v1, v2
	global_store_dwordx2 v[68:69], v[0:1], off offset:128
	v_mul_f32_e32 v0, v24, v66
	v_mul_f32_e32 v1, v25, v66
	v_cvt_pk_bf16_f32 v0, v0, v1
	v_mul_f32_e32 v1, v26, v66
	v_mul_f32_e32 v2, v27, v66
	v_cvt_pk_bf16_f32 v1, v1, v2
	global_store_dwordx2 v[68:69], v[0:1], off offset:160
	v_mul_f32_e32 v0, v20, v66
	v_mul_f32_e32 v1, v21, v66
	v_cvt_pk_bf16_f32 v0, v0, v1
	v_mul_f32_e32 v1, v22, v66
	v_mul_f32_e32 v2, v23, v66
	v_cvt_pk_bf16_f32 v1, v1, v2
	global_store_dwordx2 v[68:69], v[0:1], off offset:192
	v_mul_f32_e32 v0, v16, v66
	v_mul_f32_e32 v1, v17, v66
	v_cvt_pk_bf16_f32 v0, v0, v1
	v_mul_f32_e32 v1, v18, v66
	v_mul_f32_e32 v2, v19, v66
	v_cvt_pk_bf16_f32 v1, v1, v2
	global_store_dwordx2 v[68:69], v[0:1], off offset:224
	v_mul_f32_e32 v0, v44, v66
	v_mul_f32_e32 v1, v45, v66
	v_cvt_pk_bf16_f32 v0, v0, v1
	v_mul_f32_e32 v1, v46, v66
	v_mul_f32_e32 v2, v47, v66
	v_cvt_pk_bf16_f32 v1, v1, v2
	global_store_dwordx2 v[68:69], v[0:1], off offset:256
	v_mul_f32_e32 v0, v40, v66
	v_mul_f32_e32 v1, v41, v66
	v_cvt_pk_bf16_f32 v0, v0, v1
	v_mul_f32_e32 v1, v42, v66
	v_mul_f32_e32 v2, v43, v66
	v_cvt_pk_bf16_f32 v1, v1, v2
	global_store_dwordx2 v[68:69], v[0:1], off offset:288
	v_mul_f32_e32 v0, v36, v66
	v_mul_f32_e32 v1, v37, v66
	v_cvt_pk_bf16_f32 v0, v0, v1
	v_mul_f32_e32 v1, v38, v66
	v_mul_f32_e32 v2, v39, v66
	v_cvt_pk_bf16_f32 v1, v1, v2
	global_store_dwordx2 v[68:69], v[0:1], off offset:320
	v_mul_f32_e32 v0, v32, v66
	v_mul_f32_e32 v1, v33, v66
	v_cvt_pk_bf16_f32 v0, v0, v1
	v_mul_f32_e32 v1, v34, v66
	v_mul_f32_e32 v2, v35, v66
	v_cvt_pk_bf16_f32 v1, v1, v2
	global_store_dwordx2 v[68:69], v[0:1], off offset:352
	v_mul_f32_e32 v0, v60, v66
	v_mul_f32_e32 v1, v61, v66
	v_cvt_pk_bf16_f32 v0, v0, v1
	v_mul_f32_e32 v1, v62, v66
	v_mul_f32_e32 v2, v63, v66
	v_cvt_pk_bf16_f32 v1, v1, v2
	global_store_dwordx2 v[68:69], v[0:1], off offset:384
	v_mul_f32_e32 v0, v56, v66
	v_mul_f32_e32 v1, v57, v66
	v_cvt_pk_bf16_f32 v0, v0, v1
	v_mul_f32_e32 v1, v58, v66
	v_mul_f32_e32 v2, v59, v66
	v_cvt_pk_bf16_f32 v1, v1, v2
	global_store_dwordx2 v[68:69], v[0:1], off offset:416
	v_mul_f32_e32 v0, v52, v66
	v_mul_f32_e32 v1, v53, v66
	v_cvt_pk_bf16_f32 v0, v0, v1
	v_mul_f32_e32 v1, v54, v66
	v_mul_f32_e32 v2, v55, v66
	v_cvt_pk_bf16_f32 v1, v1, v2
	global_store_dwordx2 v[68:69], v[0:1], off offset:448
	v_mul_f32_e32 v0, v48, v66
	v_mul_f32_e32 v1, v49, v66
	v_cvt_pk_bf16_f32 v0, v0, v1
	v_mul_f32_e32 v1, v50, v66
	v_mul_f32_e32 v2, v51, v66
	v_cvt_pk_bf16_f32 v1, v1, v2
	global_store_dwordx2 v[68:69], v[0:1], off offset:480
	s_waitcnt lgkmcnt(0)
	s_cbranch_scc1 .LBB0_235
	v_readlane_b32 s16, v253, 49
	s_mov_b64 s[36:37], 0xc000800

.LBB0_359:
	s_andn2_b64 vcc, exec, s[22:23]
	s_cbranch_vccnz .LBB0_414
	v_mov_b32_e32 v0, v242
	s_load_dword s9, s[54:55], 0x0
	s_mov_b32 s3, s76
	v_readfirstlane_b32 s0, v0
	s_waitcnt lgkmcnt(0)
	s_ashr_i32 s11, s0, 6
	s_lshl_b32 s0, s3, 3
	s_add_i32 s0, s0, s11
	s_cmpk_gt_i32 s0, 0xfff
	s_cbranch_scc1 .LBB0_363
	s_lshl_b32 s2, s9, 3
	s_lshl_b32 s17, s56, 19
	s_add_u32 s18, s84, s17
	v_bfe_u32 v3, v0, 4, 2
	v_and_b32_e32 v158, 15, v0
	s_addc_u32 s19, s85, 0
	v_lshlrev_b32_e32 v208, 4, v3
	v_lshl_add_u64 v[0:1], s[18:19], 0, v[208:209]
	v_lshlrev_b32_e32 v208, 7, v158
	v_lshl_add_u64 v[0:1], v[0:1], 0, v[208:209]
	s_mov_b64 s[18:19], 0x128000
	v_lshl_add_u64 v[80:81], v[0:1], 0, s[18:19]
	s_mov_b64 s[18:19], 0x129000
	v_lshl_add_u64 v[82:83], v[0:1], 0, s[18:19]
	s_mov_b64 s[18:19], 0x129800
	v_lshl_add_u64 v[84:85], v[0:1], 0, s[18:19]
	s_mov_b64 s[18:19], 0x129040
	v_lshl_add_u64 v[104:105], v[0:1], 0, s[18:19]
	s_mov_b64 s[18:19], 0x129840
	v_lshl_add_u64 v[106:107], v[0:1], 0, s[18:19]
	s_mov_b64 s[18:19], 0x12a000
	v_lshl_add_u64 v[108:109], v[0:1], 0, s[18:19]
	s_mov_b64 s[18:19], 0x12a800
	v_lshl_add_u64 v[110:111], v[0:1], 0, s[18:19]
	s_mov_b64 s[18:19], 0x12b000
	v_lshl_add_u64 v[112:113], v[0:1], 0, s[18:19]
	s_mov_b64 s[18:19], 0x12b800
	v_lshl_add_u64 v[114:115], v[0:1], 0, s[18:19]
	s_mov_b64 s[18:19], 0x12a040
	v_lshl_add_u64 v[116:117], v[0:1], 0, s[18:19]
	s_mov_b64 s[18:19], 0x12a840
	v_lshl_add_u64 v[118:119], v[0:1], 0, s[18:19]
	s_mov_b64 s[18:19], 0x12b040
	v_lshl_add_u64 v[120:121], v[0:1], 0, s[18:19]
	s_mov_b64 s[18:19], 0x12b840
	v_lshl_add_u64 v[122:123], v[0:1], 0, s[18:19]
	s_mov_b64 s[18:19], 0x12c000
	v_lshl_add_u64 v[124:125], v[0:1], 0, s[18:19]
	s_mov_b64 s[18:19], 0x12c800
	v_lshl_add_u64 v[126:127], v[0:1], 0, s[18:19]
	s_mov_b64 s[18:19], 0x12d000
	v_lshl_add_u64 v[128:129], v[0:1], 0, s[18:19]
	s_mov_b64 s[18:19], 0x12d800
	v_lshl_add_u64 v[130:131], v[0:1], 0, s[18:19]
	s_mov_b64 s[18:19], 0x12c040
	v_lshl_add_u64 v[132:133], v[0:1], 0, s[18:19]
	s_mov_b64 s[18:19], 0x12c840
	v_lshl_add_u64 v[134:135], v[0:1], 0, s[18:19]
	s_mov_b64 s[18:19], 0x12d040
	v_lshl_add_u64 v[136:137], v[0:1], 0, s[18:19]
	s_mov_b64 s[18:19], 0x12d840
	v_lshl_add_u64 v[138:139], v[0:1], 0, s[18:19]
	s_mov_b64 s[18:19], 0x12e000
	v_lshl_add_u64 v[140:141], v[0:1], 0, s[18:19]
	s_mov_b64 s[18:19], 0x12e800
	v_lshl_add_u64 v[142:143], v[0:1], 0, s[18:19]
	s_mov_b64 s[18:19], 0x12f000
	v_lshl_add_u64 v[144:145], v[0:1], 0, s[18:19]
	s_mov_b64 s[18:19], 0x12f800
	v_lshl_add_u64 v[146:147], v[0:1], 0, s[18:19]
	s_mov_b64 s[18:19], 0x12e040
	v_lshl_add_u64 v[148:149], v[0:1], 0, s[18:19]
	s_mov_b64 s[18:19], 0x12e840
	v_lshl_add_u64 v[150:151], v[0:1], 0, s[18:19]
	s_mov_b64 s[18:19], 0x12f040
	v_lshlrev_b32_e32 v2, 2, v3
	v_lshlrev_b32_e32 v64, 18, v3
	v_lshl_add_u64 v[152:153], v[0:1], 0, s[18:19]
	s_mov_b64 s[18:19], 0x12f840
	s_lshl_b32 s3, s3, 7
	s_lshl_b32 s11, s11, 4
	v_mov_b32_e32 v65, v209
	v_or_b32_e32 v66, 0x8000, v64
	v_mov_b32_e32 v67, v209
	v_or_b32_e32 v68, 0x10000, v64
	v_mov_b32_e32 v69, v209
	v_or_b32_e32 v70, 0x18000, v64
	v_mov_b32_e32 v71, v209
	v_or_b32_e32 v72, 0x20000, v64
	v_mov_b32_e32 v73, v209
	v_or_b32_e32 v74, 0x28000, v64
	v_mov_b32_e32 v75, v209
	v_or_b32_e32 v76, 0x30000, v64
	v_mov_b32_e32 v77, v209
	v_or_b32_e32 v78, 0x38000, v64
	v_mov_b32_e32 v79, v209
	v_cmp_eq_u32_e32 vcc, 0, v3
	v_sub_u32_e32 v86, 0x100000, v64
	v_mov_b32_e32 v87, v209
	v_or_b32_e32 v88, 0x100000, v64
	v_mov_b32_e32 v89, v209
	v_xor_b32_e32 v90, 0xf8000, v64
	v_mov_b32_e32 v91, v209
	v_xor_b32_e32 v92, 0xf0000, v64
	v_mov_b32_e32 v93, v209
	v_xor_b32_e32 v94, 0xe8000, v64
	v_mov_b32_e32 v95, v209
	v_xor_b32_e32 v96, 0xe0000, v64
	v_mov_b32_e32 v97, v209
	v_xor_b32_e32 v98, 0xd8000, v64
	v_mov_b32_e32 v99, v209
	v_xor_b32_e32 v100, 0xd0000, v64
	v_mov_b32_e32 v101, v209
	v_xor_b32_e32 v102, 0xc8000, v64
	v_mov_b32_e32 v103, v209
	v_lshl_add_u64 v[154:155], v[0:1], 0, s[18:19]
	s_add_i32 s3, s3, s11
	s_lshl_b32 s9, s9, 7
	v_lshlrev_b32_e32 v156, 1, v2
	global_load_dwordx4 v[176:179], v[80:81], off offset:64
	global_load_dwordx4 v[180:183], v[80:81], off offset:2112
	global_load_dwordx4 v[184:187], v[104:105], off
	global_load_dwordx4 v[188:191], v[106:107], off
	global_load_dwordx4 v[192:195], v[116:117], off
	global_load_dwordx4 v[196:199], v[118:119], off
	global_load_dwordx4 v[200:203], v[120:121], off
	global_load_dwordx4 v[204:207], v[122:123], off
	global_load_dwordx4 v[214:217], v[132:133], off
	global_load_dwordx4 v[218:221], v[134:135], off
	global_load_dwordx4 v[222:225], v[136:137], off
	global_load_dwordx4 v[226:229], v[138:139], off
	global_load_dwordx4 v[230:233], v[148:149], off
	global_load_dwordx4 v[234:237], v[150:151], off
	global_load_dwordx4 v[238:241], v[152:153], off
	global_load_dwordx4 v[246:249], v[154:155], off
	s_waitcnt vmcnt(0)
.LBB0_362:
	s_ashr_i32 s11, s3, 31
	s_lshr_b32 s11, s11, 19
	s_add_i32 s11, s3, s11
	s_and_b32 s11, s11, 0xffffe000
	s_sub_i32 s11, s3, s11
	v_or_b32_e32 v0, s11, v158
	s_ashr_i32 s11, s0, 31
	s_lshr_b32 s11, s11, 23
	s_add_i32 s11, s0, s11
	s_ashr_i32 s11, s11, 9
	s_mul_i32 s18, s11, 0x84
	s_ashr_i32 s19, s18, 31
	v_sub_u32_e32 v1, 0, v0
	s_lshl_b64 s[18:19], s[18:19], 15
	v_and_b32_e32 v2, 0x1fff, v1
	v_ashrrev_i32_e32 v1, 31, v0
	s_add_u32 s22, s16, s18
	s_addc_u32 s23, s33, s19
	v_lshlrev_b64 v[56:57], 2, v[0:1]
	v_lshl_add_u64 v[22:23], s[22:23], 0, v[56:57]
	v_lshlrev_b32_e32 v208, 2, v2
	v_lshl_add_u64 v[0:1], v[22:23], 0, v[64:65]
	v_lshl_add_u64 v[2:3], v[22:23], 0, v[66:67]
	v_lshl_add_u64 v[4:5], v[22:23], 0, v[68:69]
	v_lshl_add_u64 v[6:7], v[22:23], 0, v[70:71]
	v_lshl_add_u64 v[8:9], v[22:23], 0, v[72:73]
	v_lshl_add_u64 v[10:11], v[22:23], 0, v[74:75]
	v_lshl_add_u64 v[12:13], v[22:23], 0, v[76:77]
	v_lshl_add_u64 v[14:15], v[22:23], 0, v[78:79]
	global_load_dword v2, v[2:3], off
	s_nop 0
	global_load_dword v0, v[0:1], off
	s_nop 0
	global_load_dword v1, v[6:7], off
	global_load_dword v3, v[4:5], off
	s_nop 0
	global_load_dword v4, v[10:11], off
	global_load_dword v5, v[8:9], off
	global_load_dword v6, v[14:15], off
	global_load_dword v7, v[12:13], off
	v_lshl_add_u64 v[20:21], s[22:23], 0, v[208:209]
	v_lshl_add_u64 v[24:25], v[20:21], 0, v[94:95]
	v_lshl_add_u64 v[26:27], v[20:21], 0, v[96:97]
	v_lshl_add_u64 v[28:29], v[20:21], 0, v[98:99]
	v_lshl_add_u64 v[30:31], v[20:21], 0, v[100:101]
	s_add_u32 s18, s22, 0x108000
	s_addc_u32 s19, s23, 0
	v_lshl_add_u64 v[38:39], s[18:19], 0, v[56:57]
	v_lshl_add_u64 v[36:37], s[18:19], 0, v[208:209]
	v_lshl_add_u64 v[40:41], v[36:37], 0, v[94:95]
	v_lshl_add_u64 v[42:43], v[36:37], 0, v[96:97]
	v_lshl_add_u64 v[44:45], v[36:37], 0, v[98:99]
	v_lshl_add_u64 v[46:47], v[36:37], 0, v[100:101]
	s_add_u32 s18, s22, 0x210000
	s_addc_u32 s19, s23, 0
	v_lshl_add_u64 v[54:55], s[18:19], 0, v[56:57]
	v_lshl_add_u64 v[52:53], s[18:19], 0, v[208:209]
	v_lshl_add_u64 v[58:59], v[52:53], 0, v[94:95]
	v_lshl_add_u64 v[60:61], v[52:53], 0, v[96:97]
	v_lshl_add_u64 v[62:63], v[52:53], 0, v[98:99]
	v_lshl_add_u64 v[160:161], v[52:53], 0, v[100:101]
	s_add_u32 s18, s22, 0x318000
	s_addc_u32 s19, s23, 0
	v_lshl_add_u64 v[166:167], s[18:19], 0, v[56:57]
	v_lshl_add_u64 v[56:57], v[166:167], 0, v[72:73]
	v_lshl_add_u64 v[164:165], s[18:19], 0, v[208:209]
	v_lshl_add_u64 v[168:169], v[164:165], 0, v[94:95]
	v_lshl_add_u64 v[170:171], v[164:165], 0, v[96:97]
	v_lshl_add_u64 v[172:173], v[164:165], 0, v[98:99]
	v_lshl_add_u64 v[174:175], v[164:165], 0, v[100:101]
	s_mov_b64 s[18:19], 0x1a000400
	s_add_i32 s0, s0, s2
	s_waitcnt vmcnt(6)
	v_cvt_pk_bf16_f32 v0, v0, v2
	s_waitcnt vmcnt(4)
	v_cvt_pk_bf16_f32 v1, v3, v1
	s_waitcnt vmcnt(2)
	v_cvt_pk_bf16_f32 v2, v5, v4
	s_waitcnt vmcnt(0)
	v_cvt_pk_bf16_f32 v3, v7, v6
	global_load_dwordx4 v[4:7], v[80:81], off
	global_load_dwordx4 v[8:11], v[80:81], off offset:2048
	global_load_dwordx4 v[12:15], v[82:83], off
	global_load_dwordx4 v[16:19], v[84:85], off
	s_waitcnt vmcnt(3)
	v_mfma_f32_16x16x32_bf16 v[4:7], v[4:7], v[0:3], 0
	s_waitcnt vmcnt(2)
	v_mfma_f32_16x16x32_bf16 v[8:11], v[8:11], v[0:3], 0
	s_waitcnt vmcnt(1)
	v_mfma_f32_16x16x32_bf16 v[12:15], v[12:15], v[0:3], 0
	s_waitcnt vmcnt(0)
	v_mfma_f32_16x16x32_bf16 v[0:3], v[16:19], v[0:3], 0
	v_lshl_add_u64 v[16:17], v[22:23], 0, v[88:89]
	v_lshl_add_u64 v[18:19], v[20:21], 0, v[86:87]
	v_cndmask_b32_e32 v17, v19, v17, vcc
	v_cndmask_b32_e32 v16, v18, v16, vcc
	v_lshl_add_u64 v[18:19], v[20:21], 0, v[90:91]
	v_lshl_add_u64 v[22:23], v[20:21], 0, v[92:93]
	v_lshl_add_u64 v[20:21], v[20:21], 0, v[102:103]
	global_load_dword v16, v[16:17], off
	s_nop 0
	global_load_dword v17, v[18:19], off
	s_nop 0
	global_load_dword v18, v[24:25], off
	global_load_dword v19, v[22:23], off
	s_nop 0
	global_load_dword v22, v[28:29], off
	global_load_dword v23, v[26:27], off
	s_nop 0
	global_load_dword v20, v[20:21], off
	s_nop 0
	global_load_dword v21, v[30:31], off
	v_lshl_add_u64 v[28:29], v[38:39], 0, v[76:77]
	v_lshl_add_u64 v[30:31], v[38:39], 0, v[78:79]
	s_waitcnt vmcnt(6)
	v_cvt_pk_bf16_f32 v16, v16, v17
	s_waitcnt vmcnt(4)
	v_cvt_pk_bf16_f32 v17, v19, v18
	s_waitcnt vmcnt(2)
	v_cvt_pk_bf16_f32 v18, v23, v22
	s_waitcnt vmcnt(0)
	v_cvt_pk_bf16_f32 v19, v21, v20
	s_waitcnt vmcnt(0)
	v_mfma_f32_16x16x32_bf16 v[24:27], v[176:179], v[16:19], v[4:7]
	s_nop 2
	v_lshl_add_u64 v[20:21], v[38:39], 0, v[72:73]
	v_lshl_add_u64 v[22:23], v[38:39], 0, v[74:75]
	s_waitcnt vmcnt(0)
	v_mfma_f32_16x16x32_bf16 v[8:11], v[180:183], v[16:19], v[8:11]
	s_waitcnt vmcnt(0)
	v_mfma_f32_16x16x32_bf16 v[4:7], v[184:187], v[16:19], v[12:15]
	s_nop 2
	s_waitcnt vmcnt(0)
	v_mfma_f32_16x16x32_bf16 v[0:3], v[188:191], v[16:19], v[0:3]
	v_lshl_add_u64 v[12:13], v[38:39], 0, v[64:65]
	v_lshl_add_u64 v[14:15], v[38:39], 0, v[66:67]
	v_lshl_add_u64 v[16:17], v[38:39], 0, v[68:69]
	v_lshl_add_u64 v[18:19], v[38:39], 0, v[70:71]
	global_load_dword v14, v[14:15], off
	s_nop 0
	global_load_dword v12, v[12:13], off
	s_nop 0
	global_load_dword v13, v[18:19], off
	global_load_dword v15, v[16:17], off
	s_nop 0
	global_load_dword v16, v[22:23], off
	global_load_dword v17, v[20:21], off
	global_load_dword v18, v[30:31], off
	global_load_dword v19, v[28:29], off
	s_waitcnt vmcnt(6)
	v_cvt_pk_bf16_f32 v12, v12, v14
	s_waitcnt vmcnt(4)
	v_cvt_pk_bf16_f32 v13, v15, v13
	s_waitcnt vmcnt(2)
	v_cvt_pk_bf16_f32 v14, v17, v16
	s_waitcnt vmcnt(0)
	v_cvt_pk_bf16_f32 v15, v19, v18
	global_load_dwordx4 v[28:31], v[112:113], off
	global_load_dwordx4 v[16:19], v[108:109], off
	global_load_dwordx4 v[20:23], v[110:111], off
	s_waitcnt vmcnt(2)
	v_mfma_f32_16x16x32_bf16 v[32:35], v[28:31], v[12:15], 0
	global_load_dwordx4 v[28:31], v[114:115], off
	s_waitcnt vmcnt(2)
	v_mfma_f32_16x16x32_bf16 v[16:19], v[16:19], v[12:15], 0
	s_waitcnt vmcnt(1)
	v_mfma_f32_16x16x32_bf16 v[20:23], v[20:23], v[12:15], 0
	s_waitcnt vmcnt(0)
	v_mfma_f32_16x16x32_bf16 v[12:15], v[28:31], v[12:15], 0
	v_lshl_add_u64 v[28:29], v[38:39], 0, v[88:89]
	v_lshl_add_u64 v[30:31], v[36:37], 0, v[86:87]
	v_cndmask_b32_e32 v29, v31, v29, vcc
	v_cndmask_b32_e32 v28, v30, v28, vcc
	v_lshl_add_u64 v[30:31], v[36:37], 0, v[90:91]
	v_lshl_add_u64 v[38:39], v[36:37], 0, v[92:93]
	v_lshl_add_u64 v[36:37], v[36:37], 0, v[102:103]
	global_load_dword v28, v[28:29], off
	s_nop 0
	global_load_dword v29, v[30:31], off
	s_nop 0
	global_load_dword v30, v[40:41], off
	global_load_dword v31, v[38:39], off
	s_nop 0
	global_load_dword v38, v[44:45], off
	global_load_dword v39, v[42:43], off
	global_load_dword v40, v[36:37], off
	global_load_dword v41, v[46:47], off
	v_lshl_add_u64 v[42:43], v[54:55], 0, v[74:75]
	v_lshl_add_u64 v[44:45], v[54:55], 0, v[76:77]
	v_lshl_add_u64 v[46:47], v[54:55], 0, v[78:79]
	s_waitcnt vmcnt(6)
	v_cvt_pk_bf16_f32 v36, v28, v29
	s_waitcnt vmcnt(4)
	v_cvt_pk_bf16_f32 v37, v31, v30
	s_waitcnt vmcnt(2)
	v_cvt_pk_bf16_f32 v38, v39, v38
	s_waitcnt vmcnt(0)
	v_cvt_pk_bf16_f32 v39, v41, v40
	v_lshl_add_u64 v[40:41], v[54:55], 0, v[72:73]
	s_waitcnt vmcnt(0)
	v_mfma_f32_16x16x32_bf16 v[28:31], v[192:195], v[36:39], v[16:19]
	s_nop 2
	s_waitcnt vmcnt(0)
	v_mfma_f32_16x16x32_bf16 v[20:23], v[196:199], v[36:39], v[20:23]
	s_waitcnt vmcnt(0)
	v_mfma_f32_16x16x32_bf16 v[16:19], v[200:203], v[36:39], v[32:35]
	s_nop 2
	s_waitcnt vmcnt(0)
	v_mfma_f32_16x16x32_bf16 v[12:15], v[204:207], v[36:39], v[12:15]
	v_lshl_add_u64 v[32:33], v[54:55], 0, v[64:65]
	v_lshl_add_u64 v[34:35], v[54:55], 0, v[66:67]
	v_lshl_add_u64 v[36:37], v[54:55], 0, v[68:69]
	v_lshl_add_u64 v[38:39], v[54:55], 0, v[70:71]
	global_load_dword v34, v[34:35], off
	s_nop 0
	global_load_dword v32, v[32:33], off
	s_nop 0
	global_load_dword v33, v[38:39], off
	global_load_dword v35, v[36:37], off
	s_nop 0
	global_load_dword v36, v[42:43], off
	global_load_dword v37, v[40:41], off
	global_load_dword v38, v[46:47], off
	global_load_dword v39, v[44:45], off
	s_waitcnt vmcnt(6)
	v_cvt_pk_bf16_f32 v32, v32, v34
	s_waitcnt vmcnt(4)
	v_cvt_pk_bf16_f32 v33, v35, v33
	s_waitcnt vmcnt(2)
	v_cvt_pk_bf16_f32 v34, v37, v36
	s_waitcnt vmcnt(0)
	v_cvt_pk_bf16_f32 v35, v39, v38
	global_load_dwordx4 v[44:47], v[128:129], off
	global_load_dwordx4 v[36:39], v[124:125], off
	global_load_dwordx4 v[40:43], v[126:127], off
	s_waitcnt vmcnt(2)
	v_mfma_f32_16x16x32_bf16 v[48:51], v[44:47], v[32:35], 0
	global_load_dwordx4 v[44:47], v[130:131], off
	s_waitcnt vmcnt(2)
	v_mfma_f32_16x16x32_bf16 v[36:39], v[36:39], v[32:35], 0
	s_waitcnt vmcnt(1)
	v_mfma_f32_16x16x32_bf16 v[40:43], v[40:43], v[32:35], 0
	s_waitcnt vmcnt(0)
	v_mfma_f32_16x16x32_bf16 v[32:35], v[44:47], v[32:35], 0
	v_lshl_add_u64 v[44:45], v[54:55], 0, v[88:89]
	v_lshl_add_u64 v[46:47], v[52:53], 0, v[86:87]
	v_cndmask_b32_e32 v45, v47, v45, vcc
	v_cndmask_b32_e32 v44, v46, v44, vcc
	v_lshl_add_u64 v[46:47], v[52:53], 0, v[90:91]
	v_lshl_add_u64 v[54:55], v[52:53], 0, v[92:93]
	v_lshl_add_u64 v[52:53], v[52:53], 0, v[102:103]
	global_load_dword v44, v[44:45], off
	s_nop 0
	global_load_dword v45, v[46:47], off
	s_nop 0
	global_load_dword v46, v[58:59], off
	global_load_dword v47, v[54:55], off
	s_nop 0
	global_load_dword v54, v[62:63], off
	global_load_dword v55, v[60:61], off
	global_load_dword v58, v[52:53], off
	global_load_dword v59, v[160:161], off
	v_lshl_add_u64 v[60:61], v[166:167], 0, v[76:77]
	v_lshl_add_u64 v[62:63], v[166:167], 0, v[78:79]
	s_waitcnt vmcnt(6)
	v_cvt_pk_bf16_f32 v52, v44, v45
	s_waitcnt vmcnt(4)
	v_cvt_pk_bf16_f32 v53, v47, v46
	s_waitcnt vmcnt(2)
	v_cvt_pk_bf16_f32 v54, v55, v54
	s_waitcnt vmcnt(0)
	v_cvt_pk_bf16_f32 v55, v59, v58
	v_lshl_add_u64 v[58:59], v[166:167], 0, v[74:75]
	s_waitcnt vmcnt(0)
	v_mfma_f32_16x16x32_bf16 v[44:47], v[214:217], v[52:55], v[36:39]
	s_nop 2
	s_waitcnt vmcnt(0)
	v_mfma_f32_16x16x32_bf16 v[40:43], v[218:221], v[52:55], v[40:43]
	s_waitcnt vmcnt(0)
	v_mfma_f32_16x16x32_bf16 v[36:39], v[222:225], v[52:55], v[48:51]
	s_nop 2
	s_waitcnt vmcnt(0)
	v_mfma_f32_16x16x32_bf16 v[32:35], v[226:229], v[52:55], v[32:35]
	v_lshl_add_u64 v[48:49], v[166:167], 0, v[64:65]
	v_lshl_add_u64 v[50:51], v[166:167], 0, v[66:67]
	v_lshl_add_u64 v[52:53], v[166:167], 0, v[68:69]
	v_lshl_add_u64 v[54:55], v[166:167], 0, v[70:71]
	global_load_dword v50, v[50:51], off
	s_nop 0
	global_load_dword v48, v[48:49], off
	s_nop 0
	global_load_dword v49, v[54:55], off
	global_load_dword v51, v[52:53], off
	s_nop 0
	global_load_dword v52, v[58:59], off
	global_load_dword v53, v[56:57], off
	global_load_dword v54, v[62:63], off
	global_load_dword v55, v[60:61], off
	s_waitcnt vmcnt(6)
	v_cvt_pk_bf16_f32 v48, v48, v50
	s_waitcnt vmcnt(4)
	v_cvt_pk_bf16_f32 v49, v51, v49
	s_waitcnt vmcnt(2)
	v_cvt_pk_bf16_f32 v50, v53, v52
	s_waitcnt vmcnt(0)
	v_cvt_pk_bf16_f32 v51, v55, v54
	global_load_dwordx4 v[60:63], v[144:145], off
	global_load_dwordx4 v[52:55], v[140:141], off
	global_load_dwordx4 v[56:59], v[142:143], off
	s_waitcnt vmcnt(2)
	v_mfma_f32_16x16x32_bf16 v[160:163], v[60:63], v[48:51], 0
	global_load_dwordx4 v[60:63], v[146:147], off
	s_waitcnt vmcnt(2)
	v_mfma_f32_16x16x32_bf16 v[52:55], v[52:55], v[48:51], 0
	s_waitcnt vmcnt(1)
	v_mfma_f32_16x16x32_bf16 v[56:59], v[56:59], v[48:51], 0
	s_waitcnt vmcnt(0)
	v_mfma_f32_16x16x32_bf16 v[48:51], v[60:63], v[48:51], 0
	v_lshl_add_u64 v[60:61], v[166:167], 0, v[88:89]
	v_lshl_add_u64 v[62:63], v[164:165], 0, v[86:87]
	v_cndmask_b32_e32 v61, v63, v61, vcc
	v_cndmask_b32_e32 v60, v62, v60, vcc
	v_lshl_add_u64 v[62:63], v[164:165], 0, v[90:91]
	v_lshl_add_u64 v[166:167], v[164:165], 0, v[92:93]
	v_lshl_add_u64 v[164:165], v[164:165], 0, v[102:103]
	global_load_dword v60, v[60:61], off
	s_nop 0
	global_load_dword v61, v[62:63], off
	s_nop 0
	global_load_dword v62, v[168:169], off
	global_load_dword v63, v[166:167], off
	global_load_dword v157, v[172:173], off
	global_load_dword v159, v[170:171], off
	s_nop 0
	global_load_dword v167, v[164:165], off
	global_load_dword v168, v[174:175], off
	s_waitcnt vmcnt(6)
	v_cvt_pk_bf16_f32 v164, v60, v61
	s_waitcnt vmcnt(4)
	v_cvt_pk_bf16_f32 v165, v63, v62
	s_waitcnt vmcnt(2)
	v_cvt_pk_bf16_f32 v166, v159, v157
	s_waitcnt vmcnt(0)
	v_cvt_pk_bf16_f32 v167, v168, v167
	v_mul_f32_e32 v157, v0, v0
	v_mul_f32_e32 v159, v1, v1
	s_waitcnt vmcnt(0)
	v_mfma_f32_16x16x32_bf16 v[60:63], v[230:233], v[164:167], v[52:55]
	s_nop 2
	s_waitcnt vmcnt(0)
	v_mfma_f32_16x16x32_bf16 v[56:59], v[234:237], v[164:167], v[56:59]
	s_waitcnt vmcnt(0)
	v_mfma_f32_16x16x32_bf16 v[52:55], v[238:241], v[164:167], v[160:163]
	s_nop 2
	s_waitcnt vmcnt(0)
	v_mfma_f32_16x16x32_bf16 v[48:51], v[246:249], v[164:167], v[48:51]
	v_mul_f32_e64 v160, v26, v26
	v_mul_f32_e64 v161, v27, v27
	v_pk_mul_f32 v[162:163], v[24:25], v[24:25]
	s_nop 0
	v_pk_mov_b32 v[164:165], v[162:163], v[160:161] op_sel:[1,0]
	v_mov_b32_e32 v163, v161
	v_pk_add_f32 v[160:161], v[164:165], v[162:163]
	v_pk_mul_f32 v[162:163], v[10:11], v[10:11]
	v_pk_mul_f32 v[164:165], v[8:9], v[8:9]
	v_pk_add_f32 v[160:161], v[160:161], v[160:161] op_sel:[0,1] op_sel_hi:[1,0]
	v_pk_mov_b32 v[166:167], v[164:165], v[162:163] op_sel:[1,0]
	v_mov_b32_e32 v165, v163
	v_pk_add_f32 v[162:163], v[166:167], v[164:165]
	v_mov_b32_e32 v161, v157
	v_pk_add_f32 v[162:163], v[162:163], v[162:163] op_sel:[0,1] op_sel_hi:[1,0]
	v_mul_f32_e32 v164, v2, v2
	v_mov_b32_e32 v163, v159
	v_pk_add_f32 v[160:161], v[160:161], v[162:163]
	v_mul_f32_e32 v162, v5, v5
	v_pk_fma_f32 v[162:163], v[4:5], v[4:5], v[162:163] op_sel_hi:[1,1,0]
	v_mul_f32_e32 v166, v3, v3
	v_mov_b32_e32 v163, v164
	v_mul_f32_e32 v164, v7, v7
	v_pk_fma_f32 v[164:165], v[6:7], v[6:7], v[164:165] op_sel_hi:[1,1,0]
	v_mul_f32_e32 v157, v16, v16
	v_mov_b32_e32 v165, v166
	v_pk_add_f32 v[162:163], v[162:163], v[164:165]
	v_pk_mul_f32 v[164:165], v[28:29], v[28:29]
	v_pk_add_f32 v[160:161], v[160:161], v[162:163]
	v_pk_mul_f32 v[162:163], v[30:31], v[30:31]
	v_mul_f32_e32 v159, v17, v17
	v_pk_mov_b32 v[166:167], v[164:165], v[162:163] op_sel:[1,0]
	v_mov_b32_e32 v165, v163
	v_pk_add_f32 v[162:163], v[166:167], v[164:165]
	v_pk_add_f32 v[160:161], v[160:161], v[160:161] op_sel:[0,1] op_sel_hi:[1,0]
	v_pk_add_f32 v[162:163], v[162:163], v[162:163] op_sel:[0,1] op_sel_hi:[1,0]
	v_mov_b32_e32 v161, v157
	v_mov_b32_e32 v163, v159
	v_pk_add_f32 v[160:161], v[160:161], v[162:163]
	v_mul_f32_e32 v162, v21, v21
	v_mul_f32_e32 v164, v18, v18
	v_pk_fma_f32 v[162:163], v[20:21], v[20:21], v[162:163] op_sel_hi:[1,1,0]
	v_mul_f32_e32 v166, v19, v19
	v_mov_b32_e32 v163, v164
	v_mul_f32_e32 v164, v23, v23
	v_pk_fma_f32 v[164:165], v[22:23], v[22:23], v[164:165] op_sel_hi:[1,1,0]
	v_mul_f32_e32 v157, v40, v40
	v_mov_b32_e32 v165, v166
	v_pk_add_f32 v[162:163], v[162:163], v[164:165]
	v_pk_mul_f32 v[164:165], v[12:13], v[12:13]
	v_pk_add_f32 v[160:161], v[160:161], v[162:163]
	v_pk_mul_f32 v[162:163], v[14:15], v[14:15]
	v_mul_f32_e32 v159, v41, v41
	v_pk_mov_b32 v[166:167], v[164:165], v[162:163] op_sel:[1,0]
	v_mov_b32_e32 v165, v163
	v_pk_add_f32 v[162:163], v[166:167], v[164:165]
	v_pk_add_f32 v[160:161], v[160:161], v[160:161] op_sel:[0,1] op_sel_hi:[1,0]
	v_pk_add_f32 v[162:163], v[162:163], v[162:163] op_sel:[0,1] op_sel_hi:[1,0]
	v_mov_b32_e32 v161, v157
	v_mov_b32_e32 v163, v159
	v_pk_add_f32 v[160:161], v[160:161], v[162:163]
	v_mul_f32_e32 v162, v45, v45
	v_mul_f32_e32 v164, v42, v42
	v_pk_fma_f32 v[162:163], v[44:45], v[44:45], v[162:163] op_sel_hi:[1,1,0]
	v_mul_f32_e32 v166, v43, v43
	v_mov_b32_e32 v163, v164
	v_mul_f32_e32 v164, v47, v47
	v_pk_fma_f32 v[164:165], v[46:47], v[46:47], v[164:165] op_sel_hi:[1,1,0]
	v_mul_f32_e32 v157, v60, v60
	v_mov_b32_e32 v165, v166
	v_pk_add_f32 v[162:163], v[162:163], v[164:165]
	v_pk_mul_f32 v[164:165], v[36:37], v[36:37]
	v_pk_add_f32 v[160:161], v[160:161], v[162:163]
	v_pk_mul_f32 v[162:163], v[38:39], v[38:39]
	v_mul_f32_e32 v159, v61, v61
	v_pk_mov_b32 v[166:167], v[164:165], v[162:163] op_sel:[1,0]
	v_mov_b32_e32 v165, v163
	v_pk_add_f32 v[162:163], v[166:167], v[164:165]
	v_pk_add_f32 v[160:161], v[160:161], v[160:161] op_sel:[0,1] op_sel_hi:[1,0]
	v_pk_add_f32 v[162:163], v[162:163], v[162:163] op_sel:[0,1] op_sel_hi:[1,0]
	v_mov_b32_e32 v161, v157
	v_mov_b32_e32 v163, v159
	v_pk_add_f32 v[160:161], v[160:161], v[162:163]
	v_mul_f32_e32 v162, v33, v33
	v_mul_f32_e32 v164, v62, v62
	v_pk_fma_f32 v[162:163], v[32:33], v[32:33], v[162:163] op_sel_hi:[1,1,0]
	v_mul_f32_e32 v166, v63, v63
	v_mov_b32_e32 v163, v164
	v_mul_f32_e32 v164, v35, v35
	v_pk_fma_f32 v[164:165], v[34:35], v[34:35], v[164:165] op_sel_hi:[1,1,0]
	v_mul_f32_e32 v157, v48, v48
	v_mov_b32_e32 v165, v166
	v_pk_add_f32 v[162:163], v[162:163], v[164:165]
	v_pk_mul_f32 v[164:165], v[56:57], v[56:57]
	v_pk_add_f32 v[160:161], v[160:161], v[162:163]
	v_pk_mul_f32 v[162:163], v[58:59], v[58:59]
	v_mul_f32_e32 v159, v49, v49
	v_pk_mov_b32 v[166:167], v[164:165], v[162:163] op_sel:[1,0]
	v_mov_b32_e32 v165, v163
	v_pk_add_f32 v[162:163], v[166:167], v[164:165]
	v_pk_add_f32 v[160:161], v[160:161], v[160:161] op_sel:[0,1] op_sel_hi:[1,0]
	v_pk_add_f32 v[162:163], v[162:163], v[162:163] op_sel:[0,1] op_sel_hi:[1,0]
	v_mov_b32_e32 v161, v157
	v_mov_b32_e32 v163, v159
	v_pk_add_f32 v[160:161], v[160:161], v[162:163]
	v_mul_f32_e32 v162, v53, v53
	v_mul_f32_e32 v164, v50, v50
	v_pk_fma_f32 v[162:163], v[52:53], v[52:53], v[162:163] op_sel_hi:[1,1,0]
	v_mul_f32_e32 v166, v51, v51
	v_mov_b32_e32 v163, v164
	v_mul_f32_e32 v164, v55, v55
	v_pk_fma_f32 v[164:165], v[54:55], v[54:55], v[164:165] op_sel_hi:[1,1,0]
	v_xor_b32_e32 v159, 16, v245
	v_mov_b32_e32 v165, v166
	v_pk_add_f32 v[162:163], v[162:163], v[164:165]
	s_nop 0
	v_pk_add_f32 v[160:161], v[160:161], v[162:163]
	s_nop 0
	v_add_f32_e32 v157, v160, v161
	v_and_b32_e32 v160, 64, v245
	v_add_u32_e32 v160, 64, v160
	v_cmp_lt_i32_e64 s[36:37], v159, v160
	s_nop 1
	v_cndmask_b32_e64 v159, v245, v159, s[36:37]
	v_lshlrev_b32_e32 v159, 2, v159
	ds_bpermute_b32 v159, v159, v157
	s_waitcnt lgkmcnt(0)
	v_add_f32_e32 v157, v157, v159
	v_xor_b32_e32 v159, 32, v245
	v_cmp_lt_i32_e64 s[36:37], v159, v160
	v_add_u32_e32 v160, s3, v158
	v_ashrrev_i32_e32 v161, 31, v160
	v_cndmask_b32_e64 v159, v245, v159, s[36:37]
	v_lshlrev_b32_e32 v159, 2, v159
	ds_bpermute_b32 v159, v159, v157
	v_lshlrev_b64 v[160:161], 11, v[160:161]
	v_lshl_add_u64 v[160:161], s[84:85], 0, v[160:161]
	s_add_i32 s3, s3, s9
	s_cmpk_lt_i32 s0, 0x1000
	s_waitcnt lgkmcnt(0)
	v_add_f32_e32 v157, v157, v159
	v_fmamk_f32 v157, v157, 0x3b800000, v244
	v_cmp_gt_f32_e64 s[36:37], s7, v157
	v_mul_f32_e32 v159, 0x4b800000, v157
	s_nop 0
	v_cndmask_b32_e64 v157, v157, v159, s[36:37]
	v_rsq_f32_e32 v157, v157
	s_nop 0
	v_mul_f32_e32 v159, 0x45800000, v157
	v_cndmask_b32_e64 v159, v157, v159, s[36:37]
	v_mov_b32_e32 v157, v209
	v_mul_f32_e32 v24, v24, v159
	v_mul_f32_e32 v25, v25, v159
	v_lshl_add_u64 v[160:161], v[160:161], 0, v[156:157]
	v_cvt_pk_bf16_f32 v24, v24, v25
	v_mul_f32_e32 v25, v26, v159
	v_mul_f32_e32 v26, v27, v159
	v_cvt_pk_bf16_f32 v25, v25, v26
	v_add_co_u32_e64 v26, s[36:37], s47, v160
	v_mul_f32_e32 v8, v8, v159
	s_nop 0
	v_addc_co_u32_e64 v27, s[36:37], 0, v161, s[36:37]
	v_mul_f32_e32 v9, v9, v159
	v_lshl_add_u64 v[162:163], v[160:161], 0, s[18:19]
	global_store_dwordx2 v[26:27], v[24:25], off offset:1024
	v_cvt_pk_bf16_f32 v8, v8, v9
	v_mul_f32_e32 v9, v10, v159
	v_mul_f32_e32 v4, v4, v159
	v_mul_f32_e32 v5, v5, v159
	v_mul_f32_e32 v10, v11, v159
	v_cvt_pk_bf16_f32 v9, v9, v10
	global_store_dwordx2 v[162:163], v[8:9], off offset:32
	v_cvt_pk_bf16_f32 v4, v4, v5
	v_mul_f32_e32 v5, v6, v159
	v_mul_f32_e32 v0, v0, v159
	v_mul_f32_e32 v1, v1, v159
	v_mul_f32_e32 v6, v7, v159
	v_cvt_pk_bf16_f32 v5, v5, v6
	global_store_dwordx2 v[162:163], v[4:5], off offset:64
	v_cvt_pk_bf16_f32 v0, v0, v1
	v_mul_f32_e32 v1, v2, v159
	v_mul_f32_e32 v2, v3, v159
	v_cvt_pk_bf16_f32 v1, v1, v2
	global_store_dwordx2 v[162:163], v[0:1], off offset:96
	v_mul_f32_e32 v0, v28, v159
	v_mul_f32_e32 v1, v29, v159
	v_cvt_pk_bf16_f32 v0, v0, v1
	v_mul_f32_e32 v1, v30, v159
	v_mul_f32_e32 v2, v31, v159
	v_cvt_pk_bf16_f32 v1, v1, v2
	global_store_dwordx2 v[162:163], v[0:1], off offset:128
	v_mul_f32_e32 v0, v20, v159
	v_mul_f32_e32 v1, v21, v159
	v_cvt_pk_bf16_f32 v0, v0, v1
	v_mul_f32_e32 v1, v22, v159
	v_mul_f32_e32 v2, v23, v159
	v_cvt_pk_bf16_f32 v1, v1, v2
	global_store_dwordx2 v[162:163], v[0:1], off offset:160
	v_mul_f32_e32 v0, v16, v159
	v_mul_f32_e32 v1, v17, v159
	v_cvt_pk_bf16_f32 v0, v0, v1
	v_mul_f32_e32 v1, v18, v159
	v_mul_f32_e32 v2, v19, v159
	v_cvt_pk_bf16_f32 v1, v1, v2
	global_store_dwordx2 v[162:163], v[0:1], off offset:192
	v_mul_f32_e32 v0, v12, v159
	v_mul_f32_e32 v1, v13, v159
	v_cvt_pk_bf16_f32 v0, v0, v1
	v_mul_f32_e32 v1, v14, v159
	v_mul_f32_e32 v2, v15, v159
	v_cvt_pk_bf16_f32 v1, v1, v2
	global_store_dwordx2 v[162:163], v[0:1], off offset:224
	v_mul_f32_e32 v0, v44, v159
	v_mul_f32_e32 v1, v45, v159
	v_cvt_pk_bf16_f32 v0, v0, v1
	v_mul_f32_e32 v1, v46, v159
	v_mul_f32_e32 v2, v47, v159
	v_cvt_pk_bf16_f32 v1, v1, v2
	global_store_dwordx2 v[162:163], v[0:1], off offset:256
	v_mul_f32_e32 v0, v40, v159
	v_mul_f32_e32 v1, v41, v159
	v_cvt_pk_bf16_f32 v0, v0, v1
	v_mul_f32_e32 v1, v42, v159
	v_mul_f32_e32 v2, v43, v159
	v_cvt_pk_bf16_f32 v1, v1, v2
	global_store_dwordx2 v[162:163], v[0:1], off offset:288
	v_mul_f32_e32 v0, v36, v159
	v_mul_f32_e32 v1, v37, v159
	v_cvt_pk_bf16_f32 v0, v0, v1
	v_mul_f32_e32 v1, v38, v159
	v_mul_f32_e32 v2, v39, v159
	v_cvt_pk_bf16_f32 v1, v1, v2
	global_store_dwordx2 v[162:163], v[0:1], off offset:320
	v_mul_f32_e32 v0, v32, v159
	v_mul_f32_e32 v1, v33, v159
	v_cvt_pk_bf16_f32 v0, v0, v1
	v_mul_f32_e32 v1, v34, v159
	v_mul_f32_e32 v2, v35, v159
	v_cvt_pk_bf16_f32 v1, v1, v2
	global_store_dwordx2 v[162:163], v[0:1], off offset:352
	v_mul_f32_e32 v0, v60, v159
	v_mul_f32_e32 v1, v61, v159
	v_cvt_pk_bf16_f32 v0, v0, v1
	v_mul_f32_e32 v1, v62, v159
	v_mul_f32_e32 v2, v63, v159
	v_cvt_pk_bf16_f32 v1, v1, v2
	global_store_dwordx2 v[162:163], v[0:1], off offset:384
	v_mul_f32_e32 v0, v56, v159
	v_mul_f32_e32 v1, v57, v159
	v_cvt_pk_bf16_f32 v0, v0, v1
	v_mul_f32_e32 v1, v58, v159
	v_mul_f32_e32 v2, v59, v159
	v_cvt_pk_bf16_f32 v1, v1, v2
	global_store_dwordx2 v[162:163], v[0:1], off offset:416
	v_mul_f32_e32 v0, v52, v159
	v_mul_f32_e32 v1, v53, v159
	v_cvt_pk_bf16_f32 v0, v0, v1
	v_mul_f32_e32 v1, v54, v159
	v_mul_f32_e32 v2, v55, v159
	v_cvt_pk_bf16_f32 v1, v1, v2
	global_store_dwordx2 v[162:163], v[0:1], off offset:448
	v_mul_f32_e32 v0, v48, v159
	v_mul_f32_e32 v1, v49, v159
	v_cvt_pk_bf16_f32 v0, v0, v1
	v_mul_f32_e32 v1, v50, v159
	v_mul_f32_e32 v2, v51, v159
	v_cvt_pk_bf16_f32 v1, v1, v2
	global_store_dwordx2 v[162:163], v[0:1], off offset:480
	s_cbranch_scc1 .LBB0_362
